# fin chunk matmul on f32 MFMA; DMA issue interleaved with MFMAs in gemm loops
# speedup vs baseline: 1.0435x; 1.0120x over previous
.LBB0_62:
	s_ashr_i32 s22, s1, 31
	s_lshr_b32 s22, s22, 27
	s_add_i32 s22, s1, s22
	s_and_b32 s23, s22, 0xffffe0
	s_sub_i32 s23, s1, s23
	s_lshl_b32 s40, s23, 8
	s_lshl_b32 s22, s22, 2
	s_ashr_i32 s41, s40, 31
	s_and_b32 s44, s22, 0xffffff80
	v_readlane_b32 s4, v254, 0
	s_ashr_i32 s45, s44, 31
	s_lshl_b64 s[22:23], s[40:41], 11
	v_readlane_b32 s6, v254, 2
	v_readlane_b32 s7, v254, 3
	s_add_u32 s22, s6, s22
	s_addc_u32 s23, s7, s23
	s_lshl_b64 s[4:5], s[44:45], 11
	s_add_u32 s4, s20, s4
	s_addc_u32 s5, s21, s5
	s_waitcnt lgkmcnt(0)
	v_lshrrev_b32_e32 v132, 3, v196
	v_lshrrev_b32_e32 v133, 4, v196
	v_xor_b32_e32 v133, v133, v196
	v_and_b32_e32 v133, 7, v133
	v_lshlrev_b32_e32 v133, 4, v133
	v_lshl_or_b32 v82, v132, 11, v133
	v_add_u32_e32 v83, 0x20000, v82
	v_add_u32_e32 v84, 0x40000, v82
	v_add_u32_e32 v85, 0x60000, v82
	v_add_u32_e32 v132, 0, v140
	v_xor_b32_e32 v132, v132, v141
	v_lshlrev_b32_e32 v132, 4, v132
	v_add3_u32 v86, v150, v132, 0
	v_add3_u32 v128, v151, v132, 0
	v_add_u32_e32 v132, 2, v140
	v_xor_b32_e32 v132, v132, v141
	v_lshlrev_b32_e32 v132, 4, v132
	v_add3_u32 v87, v150, v132, 0
	v_add3_u32 v129, v151, v132, 0
	v_add_u32_e32 v132, 4, v140
	v_xor_b32_e32 v132, v132, v141
	v_lshlrev_b32_e32 v132, 4, v132
	v_add3_u32 v88, v150, v132, 0
	v_add3_u32 v130, v151, v132, 0
	v_add_u32_e32 v132, 6, v140
	v_xor_b32_e32 v132, v132, v141
	v_lshlrev_b32_e32 v132, 4, v132
	v_add3_u32 v89, v150, v132, 0
	v_add3_u32 v131, v151, v132, 0
	v_lshrrev_b32_e32 v132, 6, v196
	v_mov_b64_e32 v[2:3], 0
	v_mov_b64_e32 v[4:5], 0
	v_mov_b64_e32 v[6:7], 0
	v_mov_b64_e32 v[8:9], 0
	v_mov_b64_e32 v[10:11], 0
	v_mov_b64_e32 v[12:13], 0
	v_mov_b64_e32 v[14:15], 0
	v_mov_b64_e32 v[16:17], 0
	v_mov_b64_e32 v[18:19], 0
	v_mov_b64_e32 v[20:21], 0
	v_mov_b64_e32 v[22:23], 0
	v_mov_b64_e32 v[24:25], 0
	v_mov_b64_e32 v[26:27], 0
	v_mov_b64_e32 v[28:29], 0
	v_mov_b64_e32 v[30:31], 0
	v_mov_b64_e32 v[32:33], 0
	v_mov_b64_e32 v[34:35], 0
	v_mov_b64_e32 v[36:37], 0
	v_mov_b64_e32 v[38:39], 0
	v_mov_b64_e32 v[40:41], 0
	v_mov_b64_e32 v[42:43], 0
	v_mov_b64_e32 v[44:45], 0
	v_mov_b64_e32 v[46:47], 0
	v_mov_b64_e32 v[48:49], 0
	v_mov_b64_e32 v[50:51], 0
	v_mov_b64_e32 v[52:53], 0
	v_mov_b64_e32 v[54:55], 0
	v_mov_b64_e32 v[56:57], 0
	v_mov_b64_e32 v[58:59], 0
	v_mov_b64_e32 v[60:61], 0
	v_mov_b64_e32 v[62:63], 0
	v_mov_b64_e32 v[64:65], 0
	v_readfirstlane_b32 s10, v132
	s_lshl_b32 s10, s10, 10
	s_add_i32 s10, s10, 16
	s_add_i32 vcc_hi, s10, 0xc000
	s_mov_b32 m0, s10
	s_nop 0
	global_load_lds_dwordx4 v82, s[22:23]
	s_add_u32 m0, m0, 0x2000
	s_nop 0
	global_load_lds_dwordx4 v83, s[22:23]
	s_add_u32 m0, m0, 0x2000
	s_nop 0
	global_load_lds_dwordx4 v84, s[22:23]
	s_add_u32 m0, m0, 0x2000
	s_nop 0
	global_load_lds_dwordx4 v85, s[22:23]
	s_add_u32 m0, m0, 0x2000
	s_nop 0
	global_load_lds_dwordx4 v82, s[4:5]
	s_add_u32 m0, m0, 0x2000
	s_nop 0
	global_load_lds_dwordx4 v83, s[4:5]
	s_add_u32 s22, s22, 0x80
	s_addc_u32 s23, s23, 0
	s_add_u32 s4, s4, 0x80
	s_addc_u32 s5, s5, 0
	s_mov_b32 m0, vcc_hi
	s_nop 0
	global_load_lds_dwordx4 v82, s[22:23]
	s_add_u32 m0, m0, 0x2000
	s_nop 0
	global_load_lds_dwordx4 v83, s[22:23]
	s_add_u32 m0, m0, 0x2000
	s_nop 0
	global_load_lds_dwordx4 v84, s[22:23]
	s_add_u32 m0, m0, 0x2000
	s_nop 0
	global_load_lds_dwordx4 v85, s[22:23]
	s_add_u32 m0, m0, 0x2000
	s_nop 0
	global_load_lds_dwordx4 v82, s[4:5]
	s_add_u32 m0, m0, 0x2000
	s_nop 0
	global_load_lds_dwordx4 v83, s[4:5]
	s_add_u32 s22, s22, 0x80
	s_addc_u32 s23, s23, 0
	s_add_u32 s4, s4, 0x80
	s_addc_u32 s5, s5, 0
	s_mov_b32 s9, 0
	s_movk_i32 s8, 14
.Lres_loop:
	s_waitcnt vmcnt(6)
	s_barrier
	s_add_i32 vcc_hi, s9, 2
	s_cmp_ge_u32 vcc_hi, 3
	s_cselect_b32 vcc_lo, 3, 0
	s_sub_i32 vcc_hi, vcc_hi, vcc_lo
	s_mul_i32 vcc_hi, vcc_hi, 0xc000
	s_add_i32 vcc_hi, vcc_hi, s10
	ds_read_b128 v[154:157], v86
	ds_read_b128 v[158:161], v86 offset:4096
	ds_read_b128 v[162:165], v128 offset:32768
	ds_read_b128 v[166:169], v128 offset:36864
	ds_read_b128 v[66:69], v87
	ds_read_b128 v[70:73], v87 offset:4096
	ds_read_b128 v[74:77], v129 offset:32768
	ds_read_b128 v[78:81], v129 offset:36864
	s_waitcnt lgkmcnt(4)
	s_setprio 1
	v_mfma_f32_32x32x16_bf16 v[50:65], v[154:157], v[162:165], v[50:65]
	s_mov_b32 m0, vcc_hi
	v_mfma_f32_32x32x16_bf16 v[18:33], v[158:161], v[162:165], v[18:33]
	global_load_lds_dwordx4 v82, s[22:23]
	s_add_u32 m0, m0, 0x2000
	v_mfma_f32_32x32x16_bf16 v[34:49], v[154:157], v[166:169], v[34:49]
	global_load_lds_dwordx4 v83, s[22:23]
	s_add_u32 m0, m0, 0x2000
	v_mfma_f32_32x32x16_bf16 v[2:17], v[158:161], v[166:169], v[2:17]
	global_load_lds_dwordx4 v84, s[22:23]
	s_add_u32 m0, m0, 0x2000
	s_nop 0
	global_load_lds_dwordx4 v85, s[22:23]
	s_add_u32 m0, m0, 0x2000
	s_nop 0
	global_load_lds_dwordx4 v82, s[4:5]
	s_add_u32 m0, m0, 0x2000
	s_nop 0
	global_load_lds_dwordx4 v83, s[4:5]
	s_add_u32 s22, s22, 0x80
	s_addc_u32 s23, s23, 0
	s_add_u32 s4, s4, 0x80
	s_addc_u32 s5, s5, 0
	s_setprio 0
	ds_read_b128 v[154:157], v88
	ds_read_b128 v[158:161], v88 offset:4096
	ds_read_b128 v[162:165], v130 offset:32768
	ds_read_b128 v[166:169], v130 offset:36864
	s_waitcnt lgkmcnt(4)
	s_setprio 1
	v_mfma_f32_32x32x16_bf16 v[50:65], v[66:69], v[74:77], v[50:65]
	v_mfma_f32_32x32x16_bf16 v[18:33], v[70:73], v[74:77], v[18:33]
	v_mfma_f32_32x32x16_bf16 v[34:49], v[66:69], v[78:81], v[34:49]
	v_mfma_f32_32x32x16_bf16 v[2:17], v[70:73], v[78:81], v[2:17]
	s_setprio 0
	ds_read_b128 v[66:69], v89
	ds_read_b128 v[70:73], v89 offset:4096
	ds_read_b128 v[74:77], v131 offset:32768
	ds_read_b128 v[78:81], v131 offset:36864
	s_waitcnt lgkmcnt(4)
	s_setprio 1
	v_mfma_f32_32x32x16_bf16 v[50:65], v[154:157], v[162:165], v[50:65]
	v_mfma_f32_32x32x16_bf16 v[18:33], v[158:161], v[162:165], v[18:33]
	v_mfma_f32_32x32x16_bf16 v[34:49], v[154:157], v[166:169], v[34:49]
	v_mfma_f32_32x32x16_bf16 v[2:17], v[158:161], v[166:169], v[2:17]
	s_setprio 0
	s_waitcnt lgkmcnt(0)
	s_setprio 1
	v_mfma_f32_32x32x16_bf16 v[50:65], v[66:69], v[74:77], v[50:65]
	v_mfma_f32_32x32x16_bf16 v[18:33], v[70:73], v[74:77], v[18:33]
	v_mfma_f32_32x32x16_bf16 v[34:49], v[66:69], v[78:81], v[34:49]
	v_mfma_f32_32x32x16_bf16 v[2:17], v[70:73], v[78:81], v[2:17]
	s_setprio 0
	s_add_i32 s9, s9, 1
	s_cmp_eq_u32 s9, 3
	s_cselect_b32 vcc_lo, 0xfffdc000, 0
	s_cselect_b32 s9, 0, s9
	s_add_i32 vcc_lo, vcc_lo, 0xc000
	v_add_u32_e32 v86, vcc_lo, v86
	v_add_u32_e32 v128, vcc_lo, v128
	v_add_u32_e32 v87, vcc_lo, v87
	v_add_u32_e32 v129, vcc_lo, v129
	v_add_u32_e32 v88, vcc_lo, v88
	v_add_u32_e32 v130, vcc_lo, v130
	v_add_u32_e32 v89, vcc_lo, v89
	v_add_u32_e32 v131, vcc_lo, v131
	s_add_i32 s8, s8, -1
	s_cmp_lg_u32 s8, 0
	s_cbranch_scc1 .Lres_loop
	s_waitcnt vmcnt(6)
	s_barrier
	ds_read_b128 v[154:157], v86
	ds_read_b128 v[158:161], v86 offset:4096
	ds_read_b128 v[162:165], v128 offset:32768
	ds_read_b128 v[166:169], v128 offset:36864
	ds_read_b128 v[66:69], v87
	ds_read_b128 v[70:73], v87 offset:4096
	ds_read_b128 v[74:77], v129 offset:32768
	ds_read_b128 v[78:81], v129 offset:36864
	s_waitcnt lgkmcnt(4)
	s_setprio 1
	v_mfma_f32_32x32x16_bf16 v[50:65], v[154:157], v[162:165], v[50:65]
	v_mfma_f32_32x32x16_bf16 v[18:33], v[158:161], v[162:165], v[18:33]
	v_mfma_f32_32x32x16_bf16 v[34:49], v[154:157], v[166:169], v[34:49]
	v_mfma_f32_32x32x16_bf16 v[2:17], v[158:161], v[166:169], v[2:17]
	s_setprio 0
	ds_read_b128 v[154:157], v88
	ds_read_b128 v[158:161], v88 offset:4096
	ds_read_b128 v[162:165], v130 offset:32768
	ds_read_b128 v[166:169], v130 offset:36864
	s_waitcnt lgkmcnt(4)
	s_setprio 1
	v_mfma_f32_32x32x16_bf16 v[50:65], v[66:69], v[74:77], v[50:65]
	v_mfma_f32_32x32x16_bf16 v[18:33], v[70:73], v[74:77], v[18:33]
	v_mfma_f32_32x32x16_bf16 v[34:49], v[66:69], v[78:81], v[34:49]
	v_mfma_f32_32x32x16_bf16 v[2:17], v[70:73], v[78:81], v[2:17]
	s_setprio 0
	ds_read_b128 v[66:69], v89
	ds_read_b128 v[70:73], v89 offset:4096
	ds_read_b128 v[74:77], v131 offset:32768
	ds_read_b128 v[78:81], v131 offset:36864
	s_waitcnt lgkmcnt(4)
	s_setprio 1
	v_mfma_f32_32x32x16_bf16 v[50:65], v[154:157], v[162:165], v[50:65]
	v_mfma_f32_32x32x16_bf16 v[18:33], v[158:161], v[162:165], v[18:33]
	v_mfma_f32_32x32x16_bf16 v[34:49], v[154:157], v[166:169], v[34:49]
	v_mfma_f32_32x32x16_bf16 v[2:17], v[158:161], v[166:169], v[2:17]
	s_setprio 0
	s_waitcnt lgkmcnt(0)
	s_setprio 1
	v_mfma_f32_32x32x16_bf16 v[50:65], v[66:69], v[74:77], v[50:65]
	v_mfma_f32_32x32x16_bf16 v[18:33], v[70:73], v[74:77], v[18:33]
	v_mfma_f32_32x32x16_bf16 v[34:49], v[66:69], v[78:81], v[34:49]
	v_mfma_f32_32x32x16_bf16 v[2:17], v[70:73], v[78:81], v[2:17]
	s_setprio 0
	s_add_i32 s9, s9, 1
	s_cmp_eq_u32 s9, 3
	s_cselect_b32 vcc_lo, 0xfffdc000, 0
	s_cselect_b32 s9, 0, s9
	s_add_i32 vcc_lo, vcc_lo, 0xc000
	v_add_u32_e32 v86, vcc_lo, v86
	v_add_u32_e32 v128, vcc_lo, v128
	v_add_u32_e32 v87, vcc_lo, v87
	v_add_u32_e32 v129, vcc_lo, v129
	v_add_u32_e32 v88, vcc_lo, v88
	v_add_u32_e32 v130, vcc_lo, v130
	v_add_u32_e32 v89, vcc_lo, v89
	v_add_u32_e32 v131, vcc_lo, v131
	s_waitcnt vmcnt(0)
	s_barrier
	ds_read_b128 v[154:157], v86
	ds_read_b128 v[158:161], v86 offset:4096
	ds_read_b128 v[162:165], v128 offset:32768
	ds_read_b128 v[166:169], v128 offset:36864
	ds_read_b128 v[66:69], v87
	ds_read_b128 v[70:73], v87 offset:4096
	ds_read_b128 v[74:77], v129 offset:32768
	ds_read_b128 v[78:81], v129 offset:36864
	s_waitcnt lgkmcnt(4)
	s_setprio 1
	v_mfma_f32_32x32x16_bf16 v[50:65], v[154:157], v[162:165], v[50:65]
	v_mfma_f32_32x32x16_bf16 v[18:33], v[158:161], v[162:165], v[18:33]
	v_mfma_f32_32x32x16_bf16 v[34:49], v[154:157], v[166:169], v[34:49]
	v_mfma_f32_32x32x16_bf16 v[2:17], v[158:161], v[166:169], v[2:17]
	s_setprio 0
	ds_read_b128 v[154:157], v88
	ds_read_b128 v[158:161], v88 offset:4096
	ds_read_b128 v[162:165], v130 offset:32768
	ds_read_b128 v[166:169], v130 offset:36864
	s_waitcnt lgkmcnt(4)
	s_setprio 1
	v_mfma_f32_32x32x16_bf16 v[50:65], v[66:69], v[74:77], v[50:65]
	v_mfma_f32_32x32x16_bf16 v[18:33], v[70:73], v[74:77], v[18:33]
	v_mfma_f32_32x32x16_bf16 v[34:49], v[66:69], v[78:81], v[34:49]
	v_mfma_f32_32x32x16_bf16 v[2:17], v[70:73], v[78:81], v[2:17]
	s_setprio 0
	ds_read_b128 v[66:69], v89
	ds_read_b128 v[70:73], v89 offset:4096
	ds_read_b128 v[74:77], v131 offset:32768
	ds_read_b128 v[78:81], v131 offset:36864
	s_waitcnt lgkmcnt(4)
	s_setprio 1
	v_mfma_f32_32x32x16_bf16 v[50:65], v[154:157], v[162:165], v[50:65]
	v_mfma_f32_32x32x16_bf16 v[18:33], v[158:161], v[162:165], v[18:33]
	v_mfma_f32_32x32x16_bf16 v[34:49], v[154:157], v[166:169], v[34:49]
	v_mfma_f32_32x32x16_bf16 v[2:17], v[158:161], v[166:169], v[2:17]
	s_setprio 0
	s_waitcnt lgkmcnt(0)
	s_setprio 1
	v_mfma_f32_32x32x16_bf16 v[50:65], v[66:69], v[74:77], v[50:65]
	v_mfma_f32_32x32x16_bf16 v[18:33], v[70:73], v[74:77], v[18:33]
	v_mfma_f32_32x32x16_bf16 v[34:49], v[66:69], v[78:81], v[34:49]
	v_mfma_f32_32x32x16_bf16 v[2:17], v[70:73], v[78:81], v[2:17]
	s_setprio 0
	s_barrier
	v_readlane_b32 s4, v254, 0
	v_readlane_b32 s5, v254, 1
	v_readlane_b32 s8, v254, 4
	v_readlane_b32 s9, v254, 5
	v_readlane_b32 s10, v254, 6
	v_readlane_b32 s11, v254, 7
	v_readlane_b32 s12, v254, 8
	v_readlane_b32 s13, v254, 9
	v_readlane_b32 s14, v254, 10
	v_readlane_b32 s15, v254, 11
	v_readlane_b32 s16, v254, 12
	v_readlane_b32 s17, v254, 13
	v_readlane_b32 s18, v254, 14
	v_readlane_b32 s19, v254, 15
	s_nop 7
	v_add_u32_e32 v70, s40, v142
	v_add_u32_e32 v66, 0xfffff000, v70
	v_lshrrev_b32_e32 v66, 11, v66
	s_movk_i32 s4, 0x1800
	v_mad_u32_u24 v76, v66, s4, s4
	s_movk_i32 s4, 0xfff
	v_cmp_lt_i32_e32 vcc, s4, v70
	v_or_b32_e32 v68, s44, v143
	s_nop 0
	v_cndmask_b32_e32 v78, 0, v76, vcc
	v_add_u32_e32 v66, v78, v68
	v_ashrrev_i32_e32 v67, 31, v66
	v_lshl_add_u64 v[66:67], v[66:67], 2, s[28:29]
	s_barrier
	global_load_dword v79, v[66:67], off
	v_readlane_b32 s4, v252, 14
	v_ashrrev_i32_e32 v69, 31, v68
	v_readlane_b32 s5, v252, 15
	v_lshl_add_u64 v[66:67], v[68:69], 2, s[42:43]
	v_mov_b32_e32 v77, 0
	s_and_b64 vcc, exec, s[4:5]
	v_mov_b32_e32 v80, 0
	s_cbranch_vccz .LBB0_96
	global_load_dword v80, v[66:67], off

.LBB0_476:
	v_and_b32_e32 v231, 31, v196
	v_bfe_u32 v232, v196, 5, 1
	v_bfe_u32 v233, v196, 7, 1
	v_bfe_u32 v234, v196, 6, 1
	v_lshl_or_b32 v235, v233, 5, v231
	v_lshl_add_u32 v235, v235, 6, v235
	v_add_u32_e32 v235, v235, v232
	v_lshl_add_u32 v235, v235, 2, s33
	v_lshl_or_b32 v236, v234, 5, v231
	v_lshl_or_b32 v237, v232, 6, v236
	v_lshl_add_u32 v237, v237, 2, s33
	v_lshl_or_b32 v238, v232, 8, v236
	v_lshl_or_b32 v238, v233, 11, v238
	v_lshl_add_u32 v238, v238, 2, s33
	v_and_b32_e32 v239, 0xff, v196
	v_lshl_add_u32 v239, v239, 6, s33
	v_mov_b64_e32 v[170:171], 0
	v_mov_b64_e32 v[172:173], 0
	v_mov_b64_e32 v[174:175], 0
	v_mov_b64_e32 v[176:177], 0
	v_mov_b64_e32 v[178:179], 0
	v_mov_b64_e32 v[180:181], 0
	v_mov_b64_e32 v[182:183], 0
	v_mov_b64_e32 v[184:185], 0
	ds_read2_b32 v[186:187], v235 offset0:0 offset1:2
	ds_read2st64_b32 v[188:189], v237 offset0:65 offset1:67
	ds_read2_b32 v[190:191], v235 offset0:4 offset1:6
	ds_read2st64_b32 v[192:193], v237 offset0:69 offset1:71
	s_waitcnt lgkmcnt(2)
	v_mfma_f32_32x32x2_f32 v[170:185], v186, v188, v[170:185]
	v_mfma_f32_32x32x2_f32 v[170:185], v187, v189, v[170:185]
	ds_read2_b32 v[186:187], v235 offset0:8 offset1:10
	ds_read2st64_b32 v[188:189], v237 offset0:73 offset1:75
	s_waitcnt lgkmcnt(2)
	v_mfma_f32_32x32x2_f32 v[170:185], v190, v192, v[170:185]
	v_mfma_f32_32x32x2_f32 v[170:185], v191, v193, v[170:185]
	ds_read2_b32 v[190:191], v235 offset0:12 offset1:14
	ds_read2st64_b32 v[192:193], v237 offset0:77 offset1:79
	s_waitcnt lgkmcnt(2)
	v_mfma_f32_32x32x2_f32 v[170:185], v186, v188, v[170:185]
	v_mfma_f32_32x32x2_f32 v[170:185], v187, v189, v[170:185]
	ds_read2_b32 v[186:187], v235 offset0:16 offset1:18
	ds_read2st64_b32 v[188:189], v237 offset0:81 offset1:83
	s_waitcnt lgkmcnt(2)
	v_mfma_f32_32x32x2_f32 v[170:185], v190, v192, v[170:185]
	v_mfma_f32_32x32x2_f32 v[170:185], v191, v193, v[170:185]
	ds_read2_b32 v[190:191], v235 offset0:20 offset1:22
	ds_read2st64_b32 v[192:193], v237 offset0:85 offset1:87
	s_waitcnt lgkmcnt(2)
	v_mfma_f32_32x32x2_f32 v[170:185], v186, v188, v[170:185]
	v_mfma_f32_32x32x2_f32 v[170:185], v187, v189, v[170:185]
	ds_read2_b32 v[186:187], v235 offset0:24 offset1:26
	ds_read2st64_b32 v[188:189], v237 offset0:89 offset1:91
	s_waitcnt lgkmcnt(2)
	v_mfma_f32_32x32x2_f32 v[170:185], v190, v192, v[170:185]
	v_mfma_f32_32x32x2_f32 v[170:185], v191, v193, v[170:185]
	ds_read2_b32 v[190:191], v235 offset0:28 offset1:30
	ds_read2st64_b32 v[192:193], v237 offset0:93 offset1:95
	s_waitcnt lgkmcnt(2)
	v_mfma_f32_32x32x2_f32 v[170:185], v186, v188, v[170:185]
	v_mfma_f32_32x32x2_f32 v[170:185], v187, v189, v[170:185]
	ds_read2_b32 v[186:187], v235 offset0:32 offset1:34
	ds_read2st64_b32 v[188:189], v237 offset0:97 offset1:99
	s_waitcnt lgkmcnt(2)
	v_mfma_f32_32x32x2_f32 v[170:185], v190, v192, v[170:185]
	v_mfma_f32_32x32x2_f32 v[170:185], v191, v193, v[170:185]
	ds_read2_b32 v[190:191], v235 offset0:36 offset1:38
	ds_read2st64_b32 v[192:193], v237 offset0:101 offset1:103
	s_waitcnt lgkmcnt(2)
	v_mfma_f32_32x32x2_f32 v[170:185], v186, v188, v[170:185]
	v_mfma_f32_32x32x2_f32 v[170:185], v187, v189, v[170:185]
	ds_read2_b32 v[186:187], v235 offset0:40 offset1:42
	ds_read2st64_b32 v[188:189], v237 offset0:105 offset1:107
	s_waitcnt lgkmcnt(2)
	v_mfma_f32_32x32x2_f32 v[170:185], v190, v192, v[170:185]
	v_mfma_f32_32x32x2_f32 v[170:185], v191, v193, v[170:185]
	ds_read2_b32 v[190:191], v235 offset0:44 offset1:46
	ds_read2st64_b32 v[192:193], v237 offset0:109 offset1:111
	s_waitcnt lgkmcnt(2)
	v_mfma_f32_32x32x2_f32 v[170:185], v186, v188, v[170:185]
	v_mfma_f32_32x32x2_f32 v[170:185], v187, v189, v[170:185]
	ds_read2_b32 v[186:187], v235 offset0:48 offset1:50
	ds_read2st64_b32 v[188:189], v237 offset0:113 offset1:115
	s_waitcnt lgkmcnt(2)
	v_mfma_f32_32x32x2_f32 v[170:185], v190, v192, v[170:185]
	v_mfma_f32_32x32x2_f32 v[170:185], v191, v193, v[170:185]
	ds_read2_b32 v[190:191], v235 offset0:52 offset1:54
	ds_read2st64_b32 v[192:193], v237 offset0:117 offset1:119
	s_waitcnt lgkmcnt(2)
	v_mfma_f32_32x32x2_f32 v[170:185], v186, v188, v[170:185]
	v_mfma_f32_32x32x2_f32 v[170:185], v187, v189, v[170:185]
	ds_read2_b32 v[186:187], v235 offset0:56 offset1:58
	ds_read2st64_b32 v[188:189], v237 offset0:121 offset1:123
	s_waitcnt lgkmcnt(2)
	v_mfma_f32_32x32x2_f32 v[170:185], v190, v192, v[170:185]
	v_mfma_f32_32x32x2_f32 v[170:185], v191, v193, v[170:185]
	ds_read2_b32 v[190:191], v235 offset0:60 offset1:62
	ds_read2st64_b32 v[192:193], v237 offset0:125 offset1:127
	s_waitcnt lgkmcnt(2)
	v_mfma_f32_32x32x2_f32 v[170:185], v186, v188, v[170:185]
	v_mfma_f32_32x32x2_f32 v[170:185], v187, v189, v[170:185]
	s_waitcnt lgkmcnt(0)
	v_mfma_f32_32x32x2_f32 v[170:185], v190, v192, v[170:185]
	v_mfma_f32_32x32x2_f32 v[170:185], v191, v193, v[170:185]
	s_nop 7
	s_nop 7
	s_nop 7
	ds_write_b32 v238, v170 offset:33024
	ds_write_b32 v238, v171 offset:33280
	ds_write_b32 v238, v172 offset:33536
	ds_write_b32 v238, v173 offset:33792
	ds_write_b32 v238, v174 offset:35072
	ds_write_b32 v238, v175 offset:35328
	ds_write_b32 v238, v176 offset:35584
	ds_write_b32 v238, v177 offset:35840
	ds_write_b32 v238, v178 offset:37120
	ds_write_b32 v238, v179 offset:37376
	ds_write_b32 v238, v180 offset:37632
	ds_write_b32 v238, v181 offset:37888
	ds_write_b32 v238, v182 offset:39168
	ds_write_b32 v238, v183 offset:39424
	ds_write_b32 v238, v184 offset:39680
	ds_write_b32 v238, v185 offset:39936
	s_waitcnt lgkmcnt(0)
	s_barrier
	ds_read_b128 v[170:173], v239 offset:33024
	ds_read_b128 v[174:177], v239 offset:33040
	ds_read_b128 v[178:181], v239 offset:33056
	ds_read_b128 v[182:185], v239 offset:33072
	s_waitcnt lgkmcnt(0)
	v_add_f32_e32 v50, v78, v170
	v_add_f32_e32 v51, v79, v171
	v_add_f32_e32 v52, v80, v172
	v_add_f32_e32 v53, v81, v173
	v_add_f32_e32 v54, v74, v174
	v_add_f32_e32 v55, v75, v175
	v_add_f32_e32 v56, v76, v176
	v_add_f32_e32 v57, v77, v177
	v_add_f32_e32 v58, v70, v178
	v_add_f32_e32 v59, v71, v179
	v_add_f32_e32 v60, v72, v180
	v_add_f32_e32 v61, v73, v181
	v_add_f32_e32 v62, v66, v182
	v_add_f32_e32 v63, v67, v183
	v_add_f32_e32 v64, v68, v184
	v_add_f32_e32 v65, v69, v185
	s_cmp_lg_u32 s1, s46
	s_cbranch_scc0 .LBB0_481
	s_mov_b32 s20, s1
	s_waitcnt vmcnt(19)
	v_mov_b64_e32 v[68:69], v[48:49]
	v_mov_b64_e32 v[66:67], v[46:47]
	s_waitcnt vmcnt(18)
	v_mov_b64_e32 v[72:73], v[44:45]
	v_mov_b64_e32 v[70:71], v[42:43]
	s_waitcnt vmcnt(17)
	v_mov_b64_e32 v[76:77], v[40:41]
	v_mov_b64_e32 v[74:75], v[38:39]
	s_waitcnt vmcnt(16)
	v_mov_b64_e32 v[80:81], v[36:37]
	v_mov_b64_e32 v[78:79], v[34:35]
	s_branch .LBB0_474

.Lw13_loop:
	s_waitcnt vmcnt(0)
	s_barrier
	ds_read_b128 v[4:7], v172
	ds_read_b128 v[8:11], v172 offset:4096
	ds_read_b128 v[12:15], v192 offset:32768
	ds_read_b128 v[246:249], v192 offset:36864
	ds_read_b128 v[214:217], v192 offset:40960
	ds_read_b128 v[218:221], v192 offset:45056
	ds_read_b128 v[144:147], v173
	ds_read_b128 v[148:151], v173 offset:4096
	ds_read_b128 v[152:155], v193 offset:32768
	ds_read_b128 v[156:159], v193 offset:36864
	ds_read_b128 v[160:163], v193 offset:40960
	ds_read_b128 v[164:167], v193 offset:45056
	s_waitcnt lgkmcnt(6)
	s_setprio 1
	v_mfma_f32_32x32x16_bf16 v[112:127], v[4:7], v[12:15], v[112:127]
	s_mov_b32 m0, s43
	v_mfma_f32_32x32x16_bf16 v[80:95], v[8:11], v[12:15], v[80:95]
	global_load_lds_dwordx4 v168, s[22:23]
	s_add_u32 m0, m0, 0x2000
	v_mfma_f32_32x32x16_bf16 v[128:143], v[4:7], v[246:249], v[128:143]
	global_load_lds_dwordx4 v169, s[22:23]
	s_add_u32 m0, m0, 0x2000
	v_mfma_f32_32x32x16_bf16 v[96:111], v[8:11], v[246:249], v[96:111]
	global_load_lds_dwordx4 v170, s[22:23]
	s_add_u32 m0, m0, 0x2000
	v_mfma_f32_32x32x16_bf16 v[64:79], v[4:7], v[214:217], v[64:79]
	global_load_lds_dwordx4 v171, s[22:23]
	s_add_u32 m0, m0, 0x2000
	v_mfma_f32_32x32x16_bf16 v[16:31], v[8:11], v[214:217], v[16:31]
	global_load_lds_dwordx4 v168, s[24:25]
	s_add_u32 m0, m0, 0x2000
	v_mfma_f32_32x32x16_bf16 v[48:63], v[4:7], v[218:221], v[48:63]
	global_load_lds_dwordx4 v169, s[24:25]
	s_add_u32 m0, m0, 0x2000
	v_mfma_f32_32x32x16_bf16 v[32:47], v[8:11], v[218:221], v[32:47]
	global_load_lds_dwordx4 v170, s[24:25]
	s_add_u32 m0, m0, 0x2000
	s_nop 0
	global_load_lds_dwordx4 v171, s[24:25]
	s_add_u32 s22, s22, 0x80
	s_addc_u32 s23, s23, 0
	s_add_u32 s24, s24, 0x80
	s_addc_u32 s25, s25, 0
	s_setprio 0
	ds_read_b128 v[4:7], v174
	ds_read_b128 v[8:11], v174 offset:4096
	ds_read_b128 v[12:15], v194 offset:32768
	ds_read_b128 v[246:249], v194 offset:36864
	ds_read_b128 v[214:217], v194 offset:40960
	ds_read_b128 v[218:221], v194 offset:45056
	s_waitcnt lgkmcnt(6)
	s_setprio 1
	v_mfma_f32_32x32x16_bf16 v[112:127], v[144:147], v[152:155], v[112:127]
	v_mfma_f32_32x32x16_bf16 v[80:95], v[148:151], v[152:155], v[80:95]
	v_mfma_f32_32x32x16_bf16 v[128:143], v[144:147], v[156:159], v[128:143]
	v_mfma_f32_32x32x16_bf16 v[96:111], v[148:151], v[156:159], v[96:111]
	v_mfma_f32_32x32x16_bf16 v[64:79], v[144:147], v[160:163], v[64:79]
	v_mfma_f32_32x32x16_bf16 v[16:31], v[148:151], v[160:163], v[16:31]
	v_mfma_f32_32x32x16_bf16 v[48:63], v[144:147], v[164:167], v[48:63]
	v_mfma_f32_32x32x16_bf16 v[32:47], v[148:151], v[164:167], v[32:47]
	s_setprio 0
	ds_read_b128 v[144:147], v175
	ds_read_b128 v[148:151], v175 offset:4096
	ds_read_b128 v[152:155], v195 offset:32768
	ds_read_b128 v[156:159], v195 offset:36864
	ds_read_b128 v[160:163], v195 offset:40960
	ds_read_b128 v[164:167], v195 offset:45056
	s_waitcnt lgkmcnt(6)
	s_setprio 1
	v_mfma_f32_32x32x16_bf16 v[112:127], v[4:7], v[12:15], v[112:127]
	v_mfma_f32_32x32x16_bf16 v[80:95], v[8:11], v[12:15], v[80:95]
	v_mfma_f32_32x32x16_bf16 v[128:143], v[4:7], v[246:249], v[128:143]
	v_mfma_f32_32x32x16_bf16 v[96:111], v[8:11], v[246:249], v[96:111]
	v_mfma_f32_32x32x16_bf16 v[64:79], v[4:7], v[214:217], v[64:79]
	v_mfma_f32_32x32x16_bf16 v[16:31], v[8:11], v[214:217], v[16:31]
	v_mfma_f32_32x32x16_bf16 v[48:63], v[4:7], v[218:221], v[48:63]
	v_mfma_f32_32x32x16_bf16 v[32:47], v[8:11], v[218:221], v[32:47]
	s_setprio 0
	s_waitcnt lgkmcnt(0)
	s_setprio 1
	v_mfma_f32_32x32x16_bf16 v[112:127], v[144:147], v[152:155], v[112:127]
	v_mfma_f32_32x32x16_bf16 v[80:95], v[148:151], v[152:155], v[80:95]
	v_mfma_f32_32x32x16_bf16 v[128:143], v[144:147], v[156:159], v[128:143]
	v_mfma_f32_32x32x16_bf16 v[96:111], v[148:151], v[156:159], v[96:111]
	v_mfma_f32_32x32x16_bf16 v[64:79], v[144:147], v[160:163], v[64:79]
	v_mfma_f32_32x32x16_bf16 v[16:31], v[148:151], v[160:163], v[16:31]
	v_mfma_f32_32x32x16_bf16 v[48:63], v[144:147], v[164:167], v[48:63]
	v_mfma_f32_32x32x16_bf16 v[32:47], v[148:151], v[164:167], v[32:47]
	s_setprio 0
	s_cmp_eq_u32 s1, 1
	s_cbranch_scc1 .Lw13_last
	s_waitcnt vmcnt(0)
	s_barrier
	ds_read_b128 v[4:7], v188
	ds_read_b128 v[8:11], v188 offset:4096
	ds_read_b128 v[12:15], v237 offset:32768
	ds_read_b128 v[246:249], v237 offset:36864
	ds_read_b128 v[214:217], v237 offset:40960
	ds_read_b128 v[218:221], v237 offset:45056
	ds_read_b128 v[144:147], v189
	ds_read_b128 v[148:151], v189 offset:4096
	ds_read_b128 v[152:155], v238 offset:32768
	ds_read_b128 v[156:159], v238 offset:36864
	ds_read_b128 v[160:163], v238 offset:40960
	ds_read_b128 v[164:167], v238 offset:45056
	s_waitcnt lgkmcnt(6)
	s_setprio 1
	v_mfma_f32_32x32x16_bf16 v[112:127], v[4:7], v[12:15], v[112:127]
	s_mov_b32 m0, s42
	v_mfma_f32_32x32x16_bf16 v[80:95], v[8:11], v[12:15], v[80:95]
	global_load_lds_dwordx4 v168, s[22:23]
	s_add_u32 m0, m0, 0x2000
	v_mfma_f32_32x32x16_bf16 v[128:143], v[4:7], v[246:249], v[128:143]
	global_load_lds_dwordx4 v169, s[22:23]
	s_add_u32 m0, m0, 0x2000
	v_mfma_f32_32x32x16_bf16 v[96:111], v[8:11], v[246:249], v[96:111]
	global_load_lds_dwordx4 v170, s[22:23]
	s_add_u32 m0, m0, 0x2000
	v_mfma_f32_32x32x16_bf16 v[64:79], v[4:7], v[214:217], v[64:79]
	global_load_lds_dwordx4 v171, s[22:23]
	s_add_u32 m0, m0, 0x2000
	v_mfma_f32_32x32x16_bf16 v[16:31], v[8:11], v[214:217], v[16:31]
	global_load_lds_dwordx4 v168, s[24:25]
	s_add_u32 m0, m0, 0x2000
	v_mfma_f32_32x32x16_bf16 v[48:63], v[4:7], v[218:221], v[48:63]
	global_load_lds_dwordx4 v169, s[24:25]
	s_add_u32 m0, m0, 0x2000
	v_mfma_f32_32x32x16_bf16 v[32:47], v[8:11], v[218:221], v[32:47]
	global_load_lds_dwordx4 v170, s[24:25]
	s_add_u32 m0, m0, 0x2000
	s_nop 0
	global_load_lds_dwordx4 v171, s[24:25]
	s_add_u32 s22, s22, 0x80
	s_addc_u32 s23, s23, 0
	s_add_u32 s24, s24, 0x80
	s_addc_u32 s25, s25, 0
	s_setprio 0
	ds_read_b128 v[4:7], v190
	ds_read_b128 v[8:11], v190 offset:4096
	ds_read_b128 v[12:15], v239 offset:32768
	ds_read_b128 v[246:249], v239 offset:36864
	ds_read_b128 v[214:217], v239 offset:40960
	ds_read_b128 v[218:221], v239 offset:45056
	s_waitcnt lgkmcnt(6)
	s_setprio 1
	v_mfma_f32_32x32x16_bf16 v[112:127], v[144:147], v[152:155], v[112:127]
	v_mfma_f32_32x32x16_bf16 v[80:95], v[148:151], v[152:155], v[80:95]
	v_mfma_f32_32x32x16_bf16 v[128:143], v[144:147], v[156:159], v[128:143]
	v_mfma_f32_32x32x16_bf16 v[96:111], v[148:151], v[156:159], v[96:111]
	v_mfma_f32_32x32x16_bf16 v[64:79], v[144:147], v[160:163], v[64:79]
	v_mfma_f32_32x32x16_bf16 v[16:31], v[148:151], v[160:163], v[16:31]
	v_mfma_f32_32x32x16_bf16 v[48:63], v[144:147], v[164:167], v[48:63]
	v_mfma_f32_32x32x16_bf16 v[32:47], v[148:151], v[164:167], v[32:47]
	s_setprio 0
	ds_read_b128 v[144:147], v191
	ds_read_b128 v[148:151], v191 offset:4096
	ds_read_b128 v[152:155], v240 offset:32768
	ds_read_b128 v[156:159], v240 offset:36864
	ds_read_b128 v[160:163], v240 offset:40960
	ds_read_b128 v[164:167], v240 offset:45056
	s_waitcnt lgkmcnt(6)
	s_setprio 1
	v_mfma_f32_32x32x16_bf16 v[112:127], v[4:7], v[12:15], v[112:127]
	v_mfma_f32_32x32x16_bf16 v[80:95], v[8:11], v[12:15], v[80:95]
	v_mfma_f32_32x32x16_bf16 v[128:143], v[4:7], v[246:249], v[128:143]
	v_mfma_f32_32x32x16_bf16 v[96:111], v[8:11], v[246:249], v[96:111]
	v_mfma_f32_32x32x16_bf16 v[64:79], v[4:7], v[214:217], v[64:79]
	v_mfma_f32_32x32x16_bf16 v[16:31], v[8:11], v[214:217], v[16:31]
	v_mfma_f32_32x32x16_bf16 v[48:63], v[4:7], v[218:221], v[48:63]
	v_mfma_f32_32x32x16_bf16 v[32:47], v[8:11], v[218:221], v[32:47]
	s_setprio 0
	s_waitcnt lgkmcnt(0)
	s_setprio 1
	v_mfma_f32_32x32x16_bf16 v[112:127], v[144:147], v[152:155], v[112:127]
	v_mfma_f32_32x32x16_bf16 v[80:95], v[148:151], v[152:155], v[80:95]
	v_mfma_f32_32x32x16_bf16 v[128:143], v[144:147], v[156:159], v[128:143]
	v_mfma_f32_32x32x16_bf16 v[96:111], v[148:151], v[156:159], v[96:111]
	v_mfma_f32_32x32x16_bf16 v[64:79], v[144:147], v[160:163], v[64:79]
	v_mfma_f32_32x32x16_bf16 v[16:31], v[148:151], v[160:163], v[16:31]
	v_mfma_f32_32x32x16_bf16 v[48:63], v[144:147], v[164:167], v[48:63]
	v_mfma_f32_32x32x16_bf16 v[32:47], v[148:151], v[164:167], v[32:47]
	s_setprio 0
	s_add_i32 s1, s1, -1
	s_branch .Lw13_loop
.Lw13_last:
	s_waitcnt vmcnt(0)
	s_barrier
	ds_read_b128 v[4:7], v188
	ds_read_b128 v[8:11], v188 offset:4096
	ds_read_b128 v[12:15], v237 offset:32768
	ds_read_b128 v[246:249], v237 offset:36864
	ds_read_b128 v[214:217], v237 offset:40960
	ds_read_b128 v[218:221], v237 offset:45056
	ds_read_b128 v[144:147], v189
	ds_read_b128 v[148:151], v189 offset:4096
	ds_read_b128 v[152:155], v238 offset:32768
	ds_read_b128 v[156:159], v238 offset:36864
	ds_read_b128 v[160:163], v238 offset:40960
	ds_read_b128 v[164:167], v238 offset:45056
	s_waitcnt lgkmcnt(6)
	s_setprio 1
	v_mfma_f32_32x32x16_bf16 v[112:127], v[4:7], v[12:15], v[112:127]
	v_mfma_f32_32x32x16_bf16 v[80:95], v[8:11], v[12:15], v[80:95]
	v_mfma_f32_32x32x16_bf16 v[128:143], v[4:7], v[246:249], v[128:143]
	v_mfma_f32_32x32x16_bf16 v[96:111], v[8:11], v[246:249], v[96:111]
	v_mfma_f32_32x32x16_bf16 v[64:79], v[4:7], v[214:217], v[64:79]
	v_mfma_f32_32x32x16_bf16 v[16:31], v[8:11], v[214:217], v[16:31]
	v_mfma_f32_32x32x16_bf16 v[48:63], v[4:7], v[218:221], v[48:63]
	v_mfma_f32_32x32x16_bf16 v[32:47], v[8:11], v[218:221], v[32:47]
	s_setprio 0
	ds_read_b128 v[4:7], v190
	ds_read_b128 v[8:11], v190 offset:4096
	ds_read_b128 v[12:15], v239 offset:32768
	ds_read_b128 v[246:249], v239 offset:36864
	ds_read_b128 v[214:217], v239 offset:40960
	ds_read_b128 v[218:221], v239 offset:45056
	s_waitcnt lgkmcnt(6)
	s_setprio 1
	v_mfma_f32_32x32x16_bf16 v[112:127], v[144:147], v[152:155], v[112:127]
	v_mfma_f32_32x32x16_bf16 v[80:95], v[148:151], v[152:155], v[80:95]
	v_mfma_f32_32x32x16_bf16 v[128:143], v[144:147], v[156:159], v[128:143]
	v_mfma_f32_32x32x16_bf16 v[96:111], v[148:151], v[156:159], v[96:111]
	v_mfma_f32_32x32x16_bf16 v[64:79], v[144:147], v[160:163], v[64:79]
	v_mfma_f32_32x32x16_bf16 v[16:31], v[148:151], v[160:163], v[16:31]
	v_mfma_f32_32x32x16_bf16 v[48:63], v[144:147], v[164:167], v[48:63]
	v_mfma_f32_32x32x16_bf16 v[32:47], v[148:151], v[164:167], v[32:47]
	s_setprio 0
	ds_read_b128 v[144:147], v191
	ds_read_b128 v[148:151], v191 offset:4096
	ds_read_b128 v[152:155], v240 offset:32768
	ds_read_b128 v[156:159], v240 offset:36864
	ds_read_b128 v[160:163], v240 offset:40960
	ds_read_b128 v[164:167], v240 offset:45056
	s_waitcnt lgkmcnt(6)
	s_setprio 1
	v_mfma_f32_32x32x16_bf16 v[112:127], v[4:7], v[12:15], v[112:127]
	v_mfma_f32_32x32x16_bf16 v[80:95], v[8:11], v[12:15], v[80:95]
	v_mfma_f32_32x32x16_bf16 v[128:143], v[4:7], v[246:249], v[128:143]
	v_mfma_f32_32x32x16_bf16 v[96:111], v[8:11], v[246:249], v[96:111]
	v_mfma_f32_32x32x16_bf16 v[64:79], v[4:7], v[214:217], v[64:79]
	v_mfma_f32_32x32x16_bf16 v[16:31], v[8:11], v[214:217], v[16:31]
	v_mfma_f32_32x32x16_bf16 v[48:63], v[4:7], v[218:221], v[48:63]
	v_mfma_f32_32x32x16_bf16 v[32:47], v[8:11], v[218:221], v[32:47]
	s_setprio 0
	s_waitcnt lgkmcnt(0)
	s_setprio 1
	v_mfma_f32_32x32x16_bf16 v[112:127], v[144:147], v[152:155], v[112:127]
	v_mfma_f32_32x32x16_bf16 v[80:95], v[148:151], v[152:155], v[80:95]
	v_mfma_f32_32x32x16_bf16 v[128:143], v[144:147], v[156:159], v[128:143]
	v_mfma_f32_32x32x16_bf16 v[96:111], v[148:151], v[156:159], v[96:111]
	v_mfma_f32_32x32x16_bf16 v[64:79], v[144:147], v[160:163], v[64:79]
	v_mfma_f32_32x32x16_bf16 v[16:31], v[148:151], v[160:163], v[16:31]
	v_mfma_f32_32x32x16_bf16 v[48:63], v[144:147], v[164:167], v[48:63]
	v_mfma_f32_32x32x16_bf16 v[32:47], v[148:151], v[164:167], v[32:47]
	s_setprio 0
	s_nop 7
	v_mul_f32_e32 v2, 0xbfb8aa3b, v112
	v_exp_f32_e32 v4, v2
	v_or_b32_e32 v2, s0, v234
	v_ashrrev_i32_e32 v2, 1, v2
	v_ashrrev_i32_e32 v3, 31, v2
	v_add_f32_e32 v4, 1.0, v4
	s_waitcnt vmcnt(7)
	v_lshl_add_u64 v[144:145], v[2:3], 1, v[176:177]
	v_add_u32_e32 v0, s20, v233
	s_movk_i32 s7, 0x1600
	v_mul_f32_e32 v3, 0xbfb8aa3b, v113
	v_exp_f32_e32 v3, v3
	v_rcp_f32_e32 v2, v4
	s_nop 0
	v_mul_f32_e32 v2, v112, v2
	v_mad_i64_i32 v[146:147], s[0:1], v0, s7, v[144:145]
	v_mul_f32_e32 v2, v128, v2
	v_add_f32_e32 v5, 1.0, v3
	v_cvt_pk_bf16_f32 v4, v2, s0
	v_mov_b32_e32 v179, v1
	v_lshl_add_u64 v[2:3], v[146:147], 0, v[178:179]
	global_store_short v[2:3], v4, off
	v_rcp_f32_e32 v4, v5
	v_mul_f32_e32 v5, 0xbfb8aa3b, v114
	v_exp_f32_e32 v5, v5
	v_mul_f32_e32 v4, v113, v4
	v_mul_f32_e32 v4, v129, v4
	v_cvt_pk_bf16_f32 v6, v4, s0
	v_add_f32_e32 v7, 1.0, v5
	s_movk_i32 s4, 0x1000
	v_add_co_u32_e32 v4, vcc, s4, v2
	s_movk_i32 s5, 0x2000
	s_nop 0
	v_addc_co_u32_e32 v5, vcc, 0, v3, vcc
	global_store_short v[4:5], v6, off offset:1536
	v_rcp_f32_e32 v6, v7
	v_mul_f32_e32 v7, 0xbfb8aa3b, v115
	v_exp_f32_e32 v7, v7
	v_mul_f32_e32 v6, v114, v6
	v_mul_f32_e32 v6, v130, v6
	v_cvt_pk_bf16_f32 v8, v6, s0
	v_add_f32_e32 v9, 1.0, v7
	v_add_co_u32_e32 v6, vcc, s5, v2
	v_mov_b32_e32 v181, v1
	s_nop 0
	v_addc_co_u32_e32 v7, vcc, 0, v3, vcc
	global_store_short v[6:7], v8, off offset:3072
	v_rcp_f32_e32 v8, v9
	v_mul_f32_e32 v9, 0xbfb8aa3b, v116
	v_exp_f32_e32 v9, v9
	v_mul_f32_e32 v8, v115, v8
	v_mul_f32_e32 v8, v131, v8
	v_cvt_pk_bf16_f32 v10, v8, s0
	v_add_f32_e32 v11, 1.0, v9
	v_lshl_add_u64 v[8:9], v[146:147], 0, v[180:181]
	global_store_short v[8:9], v10, off
	s_mov_b32 s8, 0xb000
	v_rcp_f32_e32 v10, v11
	v_mul_f32_e32 v11, 0xbfb8aa3b, v117
	v_exp_f32_e32 v11, v11
	v_mul_f32_e32 v10, v116, v10
	v_mul_f32_e32 v10, v132, v10
	v_cvt_pk_bf16_f32 v12, v10, s0
	v_add_f32_e32 v13, 1.0, v11
	v_add_co_u32_e32 v10, vcc, s8, v2
	s_mov_b32 s6, 0xd000
	s_nop 0
	v_addc_co_u32_e32 v11, vcc, 0, v3, vcc
	global_store_short v[10:11], v12, off
	v_rcp_f32_e32 v12, v13
	v_mul_f32_e32 v13, 0xbfb8aa3b, v118
	v_exp_f32_e32 v13, v13
	v_mul_f32_e32 v12, v117, v12
	v_mul_f32_e32 v12, v133, v12
	v_cvt_pk_bf16_f32 v14, v12, s0
	v_add_f32_e32 v15, 1.0, v13
	v_add_co_u32_e32 v12, vcc, s36, v2
	v_mov_b32_e32 v183, v1
	s_nop 0
	v_addc_co_u32_e32 v13, vcc, 0, v3, vcc
	global_store_short v[12:13], v14, off offset:1536
	v_rcp_f32_e32 v14, v15
	v_mul_f32_e32 v15, 0xbfb8aa3b, v119
	v_exp_f32_e32 v15, v15
	v_mul_f32_e32 v14, v118, v14
	v_mul_f32_e32 v14, v134, v14
	v_cvt_pk_bf16_f32 v112, v14, s0
	v_add_f32_e32 v113, 1.0, v15
	v_add_co_u32_e32 v14, vcc, s6, v2
	s_mov_b32 s9, 0x16000
	s_nop 0
	v_addc_co_u32_e32 v15, vcc, 0, v3, vcc
	global_store_short v[14:15], v112, off offset:3072
	v_rcp_f32_e32 v112, v113
	v_mul_f32_e32 v113, 0xbfb8aa3b, v120
	v_exp_f32_e32 v113, v113
	v_mul_f32_e32 v112, v119, v112
	v_mul_f32_e32 v112, v135, v112
	v_cvt_pk_bf16_f32 v114, v112, s0
	v_add_f32_e32 v115, 1.0, v113
	v_lshl_add_u64 v[112:113], v[146:147], 0, v[182:183]
	global_store_short v[112:113], v114, off
	s_mov_b32 s10, 0x17000
	v_rcp_f32_e32 v114, v115
	v_mul_f32_e32 v115, 0xbfb8aa3b, v121
	v_exp_f32_e32 v115, v115
	v_mul_f32_e32 v114, v120, v114
	v_mul_f32_e32 v114, v136, v114
	v_cvt_pk_bf16_f32 v116, v114, s0
	v_add_f32_e32 v117, 1.0, v115
	v_add_co_u32_e32 v114, vcc, s9, v2
	v_mov_b32_e32 v185, v1
	s_nop 0
	v_addc_co_u32_e32 v115, vcc, 0, v3, vcc
	global_store_short v[114:115], v116, off
	v_rcp_f32_e32 v116, v117
	v_mul_f32_e32 v117, 0xbfb8aa3b, v122
	v_exp_f32_e32 v117, v117
	v_mul_f32_e32 v116, v121, v116
	v_mul_f32_e32 v116, v137, v116
	v_cvt_pk_bf16_f32 v118, v116, s0
	v_add_f32_e32 v119, 1.0, v117
	v_add_co_u32_e32 v116, vcc, s10, v2
	s_mov_b32 s11, 0x21000
	s_nop 0
	v_addc_co_u32_e32 v117, vcc, 0, v3, vcc
	global_store_short v[116:117], v118, off offset:1536
	v_rcp_f32_e32 v118, v119
	v_mul_f32_e32 v119, 0xbfb8aa3b, v123
	v_exp_f32_e32 v119, v119
	v_mul_f32_e32 v118, v122, v118
	v_mul_f32_e32 v118, v138, v118
	v_cvt_pk_bf16_f32 v120, v118, s0
	v_add_f32_e32 v121, 1.0, v119
	v_add_co_u32_e32 v118, vcc, s35, v2
	s_mov_b32 s12, 0x22000
	s_nop 0
	v_addc_co_u32_e32 v119, vcc, 0, v3, vcc
	global_store_short v[118:119], v120, off offset:3072
	v_rcp_f32_e32 v120, v121
	v_mul_f32_e32 v121, 0xbfb8aa3b, v124
	v_exp_f32_e32 v121, v121
	v_mul_f32_e32 v120, v123, v120
	v_mul_f32_e32 v120, v139, v120
	v_cvt_pk_bf16_f32 v122, v120, s0
	v_add_f32_e32 v123, 1.0, v121
	v_lshl_add_u64 v[120:121], v[146:147], 0, v[184:185]
	global_store_short v[120:121], v122, off
	s_mov_b32 s13, 0x23000
	v_rcp_f32_e32 v122, v123
	v_mul_f32_e32 v123, 0xbfb8aa3b, v125
	v_exp_f32_e32 v123, v123
	v_mul_f32_e32 v122, v124, v122
	v_mul_f32_e32 v122, v140, v122
	v_cvt_pk_bf16_f32 v124, v122, s0
	v_add_f32_e32 v128, 1.0, v123
	v_add_co_u32_e32 v122, vcc, s11, v2
	v_mov_b32_e32 v187, v1
	s_nop 0
	v_addc_co_u32_e32 v123, vcc, 0, v3, vcc
	global_store_short v[122:123], v124, off
	v_rcp_f32_e32 v124, v128
	v_mul_f32_e32 v128, 0xbfb8aa3b, v126
	v_exp_f32_e32 v128, v128
	v_mul_f32_e32 v124, v125, v124
	v_mul_f32_e32 v124, v141, v124
	v_cvt_pk_bf16_f32 v129, v124, s0
	v_add_f32_e32 v128, 1.0, v128
	v_add_co_u32_e32 v124, vcc, s12, v2
	v_or_b32_e32 v0, 32, v0
	s_nop 0
	v_addc_co_u32_e32 v125, vcc, 0, v3, vcc
	global_store_short v[124:125], v129, off offset:1536
	v_rcp_f32_e32 v128, v128
	v_mul_f32_e32 v129, 0xbfb8aa3b, v127
	v_exp_f32_e32 v129, v129
	v_mul_f32_e32 v126, v126, v128
	v_mul_f32_e32 v126, v142, v126
	v_cvt_pk_bf16_f32 v126, v126, s0
	v_add_f32_e32 v130, 1.0, v129
	v_add_co_u32_e32 v128, vcc, s13, v2
	s_add_i32 s30, s30, s27
	s_nop 0
	v_addc_co_u32_e32 v129, vcc, 0, v3, vcc
	global_store_short v[128:129], v126, off offset:3072
	v_rcp_f32_e32 v126, v130
	s_nop 0
	v_mul_f32_e32 v126, v127, v126
	v_mul_f32_e32 v126, v143, v126
	v_cvt_pk_bf16_f32 v130, v126, s0
	v_mul_f32_e32 v126, 0xbfb8aa3b, v80
	v_exp_f32_e32 v131, v126
	v_lshl_add_u64 v[126:127], v[146:147], 0, v[186:187]
	global_store_short v[126:127], v130, off
	v_mad_i64_i32 v[132:133], s[0:1], v0, s7, v[144:145]
	v_add_f32_e32 v130, 1.0, v131
	s_cmpk_gt_i32 s30, 0x2bf
	v_mul_f32_e32 v131, 0xbfb8aa3b, v81
	v_exp_f32_e32 v131, v131
	v_rcp_f32_e32 v0, v130
	s_nop 0
	v_mul_f32_e32 v0, v80, v0
	v_add_f32_e32 v80, 1.0, v131
	v_mul_f32_e32 v0, v96, v0
	s_nop 0
	v_cvt_pk_bf16_f32 v0, v0, s0
	v_lshl_add_u64 v[130:131], v[132:133], 0, v[178:179]
	global_store_short v[130:131], v0, off
	v_rcp_f32_e32 v0, v80
	v_mul_f32_e32 v80, 0xbfb8aa3b, v82
	v_exp_f32_e32 v80, v80
	v_mul_f32_e32 v0, v81, v0
	v_mul_f32_e32 v0, v97, v0
	v_cvt_pk_bf16_f32 v0, v0, s0
	v_add_f32_e32 v96, 1.0, v80
	v_add_co_u32_e32 v80, vcc, s4, v130
	s_nop 1
	v_addc_co_u32_e32 v81, vcc, 0, v131, vcc
	global_store_short v[80:81], v0, off offset:1536
	v_rcp_f32_e32 v0, v96
	v_mul_f32_e32 v96, 0xbfb8aa3b, v83
	v_exp_f32_e32 v96, v96
	v_mul_f32_e32 v0, v82, v0
	v_mul_f32_e32 v0, v98, v0
	v_cvt_pk_bf16_f32 v0, v0, s0
	v_add_f32_e32 v82, 1.0, v96
	v_add_co_u32_e32 v96, vcc, s5, v130
	s_nop 1
	v_addc_co_u32_e32 v97, vcc, 0, v131, vcc
	global_store_short v[96:97], v0, off offset:3072
	v_mul_f32_e32 v98, 0xbfb8aa3b, v84
	v_exp_f32_e32 v98, v98
	v_rcp_f32_e32 v0, v82
	s_nop 0
	v_mul_f32_e32 v0, v83, v0
	v_add_f32_e32 v98, 1.0, v98
	v_mul_f32_e32 v0, v99, v0
	s_nop 0
	v_cvt_pk_bf16_f32 v0, v0, s0
	v_lshl_add_u64 v[82:83], v[132:133], 0, v[180:181]
	global_store_short v[82:83], v0, off
	v_rcp_f32_e32 v0, v98
	v_mul_f32_e32 v98, 0xbfb8aa3b, v85
	v_exp_f32_e32 v98, v98
	v_mul_f32_e32 v0, v84, v0
	v_mul_f32_e32 v0, v100, v0
	v_cvt_pk_bf16_f32 v0, v0, s0
	v_add_f32_e32 v84, 1.0, v98
	v_add_co_u32_e32 v98, vcc, s8, v130
	s_nop 1
	v_addc_co_u32_e32 v99, vcc, 0, v131, vcc
	global_store_short v[98:99], v0, off
	v_rcp_f32_e32 v0, v84
	v_mul_f32_e32 v84, 0xbfb8aa3b, v86
	v_exp_f32_e32 v84, v84
	v_mul_f32_e32 v0, v85, v0
	v_mul_f32_e32 v0, v101, v0
	v_cvt_pk_bf16_f32 v0, v0, s0
	v_add_f32_e32 v100, 1.0, v84
	v_add_co_u32_e32 v84, vcc, s36, v130
	s_nop 1
	v_addc_co_u32_e32 v85, vcc, 0, v131, vcc
	global_store_short v[84:85], v0, off offset:1536
	v_rcp_f32_e32 v0, v100
	v_mul_f32_e32 v100, 0xbfb8aa3b, v87
	v_exp_f32_e32 v100, v100
	v_mul_f32_e32 v0, v86, v0
	v_mul_f32_e32 v0, v102, v0
	v_cvt_pk_bf16_f32 v0, v0, s0
	v_add_f32_e32 v86, 1.0, v100
	v_add_co_u32_e32 v100, vcc, s6, v130
	s_nop 1
	v_addc_co_u32_e32 v101, vcc, 0, v131, vcc
	global_store_short v[100:101], v0, off offset:3072
	v_mul_f32_e32 v102, 0xbfb8aa3b, v88
	v_exp_f32_e32 v102, v102
	v_rcp_f32_e32 v0, v86
	s_nop 0
	v_mul_f32_e32 v0, v87, v0
	v_add_f32_e32 v102, 1.0, v102
	v_mul_f32_e32 v0, v103, v0
	s_nop 0
	v_cvt_pk_bf16_f32 v0, v0, s0
	v_lshl_add_u64 v[86:87], v[132:133], 0, v[182:183]
	global_store_short v[86:87], v0, off
	v_rcp_f32_e32 v0, v102
	v_mul_f32_e32 v102, 0xbfb8aa3b, v89
	v_exp_f32_e32 v102, v102
	v_mul_f32_e32 v0, v88, v0
	v_mul_f32_e32 v0, v104, v0
	v_cvt_pk_bf16_f32 v0, v0, s0
	v_add_f32_e32 v88, 1.0, v102
	v_add_co_u32_e32 v102, vcc, s9, v130
	s_nop 1
	v_addc_co_u32_e32 v103, vcc, 0, v131, vcc
	global_store_short v[102:103], v0, off
	v_rcp_f32_e32 v0, v88
	v_mul_f32_e32 v88, 0xbfb8aa3b, v90
	v_exp_f32_e32 v88, v88
	v_mul_f32_e32 v0, v89, v0
	v_mul_f32_e32 v0, v105, v0
	v_cvt_pk_bf16_f32 v0, v0, s0
	v_add_f32_e32 v104, 1.0, v88
	v_add_co_u32_e32 v88, vcc, s10, v130
	s_nop 1
	v_addc_co_u32_e32 v89, vcc, 0, v131, vcc
	global_store_short v[88:89], v0, off offset:1536
	v_rcp_f32_e32 v0, v104
	v_mul_f32_e32 v104, 0xbfb8aa3b, v91
	v_exp_f32_e32 v104, v104
	v_mul_f32_e32 v0, v90, v0
	v_mul_f32_e32 v0, v106, v0
	v_cvt_pk_bf16_f32 v0, v0, s0
	v_add_f32_e32 v90, 1.0, v104
	v_add_co_u32_e32 v104, vcc, s35, v130
	s_nop 1
	v_addc_co_u32_e32 v105, vcc, 0, v131, vcc
	global_store_short v[104:105], v0, off offset:3072
	v_mul_f32_e32 v106, 0xbfb8aa3b, v92
	v_exp_f32_e32 v106, v106
	v_rcp_f32_e32 v0, v90
	s_nop 0
	v_mul_f32_e32 v0, v91, v0
	v_add_f32_e32 v106, 1.0, v106
	v_mul_f32_e32 v0, v107, v0
	s_nop 0
	v_cvt_pk_bf16_f32 v0, v0, s0
	v_lshl_add_u64 v[90:91], v[132:133], 0, v[184:185]
	global_store_short v[90:91], v0, off
	v_rcp_f32_e32 v0, v106
	v_mul_f32_e32 v106, 0xbfb8aa3b, v93
	v_exp_f32_e32 v106, v106
	v_mul_f32_e32 v0, v92, v0
	v_mul_f32_e32 v0, v108, v0
	v_cvt_pk_bf16_f32 v0, v0, s0
	v_add_f32_e32 v92, 1.0, v106
	v_add_co_u32_e32 v106, vcc, s11, v130
	s_nop 1
	v_addc_co_u32_e32 v107, vcc, 0, v131, vcc
	global_store_short v[106:107], v0, off
	v_rcp_f32_e32 v0, v92
	v_mul_f32_e32 v92, 0xbfb8aa3b, v94
	v_exp_f32_e32 v92, v92
	v_mul_f32_e32 v0, v93, v0
	v_mul_f32_e32 v0, v109, v0
	v_cvt_pk_bf16_f32 v0, v0, s0
	v_add_f32_e32 v108, 1.0, v92
	v_add_co_u32_e32 v92, vcc, s12, v130
	s_nop 1
	v_addc_co_u32_e32 v93, vcc, 0, v131, vcc
	global_store_short v[92:93], v0, off offset:1536
	v_rcp_f32_e32 v0, v108
	v_mul_f32_e32 v108, 0xbfb8aa3b, v95
	v_exp_f32_e32 v108, v108
	v_mul_f32_e32 v0, v94, v0
	v_mul_f32_e32 v0, v110, v0
	v_cvt_pk_bf16_f32 v0, v0, s0
	v_add_f32_e32 v94, 1.0, v108
	v_add_co_u32_e32 v108, vcc, s13, v130
	s_nop 1
	v_addc_co_u32_e32 v109, vcc, 0, v131, vcc
	global_store_short v[108:109], v0, off offset:3072
	v_mul_f32_e32 v110, 0xbfb8aa3b, v64
	v_exp_f32_e32 v110, v110
	v_rcp_f32_e32 v0, v94
	s_nop 0
	v_mul_f32_e32 v0, v95, v0
	v_add_f32_e32 v110, 1.0, v110
	v_mul_f32_e32 v0, v111, v0
	s_nop 0
	v_cvt_pk_bf16_f32 v0, v0, s0
	v_lshl_add_u64 v[94:95], v[132:133], 0, v[186:187]
	global_store_short v[94:95], v0, off
	v_mul_f32_e32 v111, 0xbfb8aa3b, v65
	v_exp_f32_e32 v111, v111
	v_rcp_f32_e32 v0, v110
	s_nop 0
	v_mul_f32_e32 v0, v64, v0
	v_add_f32_e32 v64, 1.0, v111
	v_mul_f32_e32 v0, v48, v0
	v_cvt_pk_bf16_f32 v0, v0, s0
	global_store_short v[2:3], v0, off offset:64
	v_mul_f32_e32 v3, 0xbfb8aa3b, v66
	v_exp_f32_e32 v3, v3
	v_rcp_f32_e32 v0, v64
	v_add_f32_e32 v2, 1.0, v3
	v_mul_f32_e32 v0, v65, v0
	v_mul_f32_e32 v0, v49, v0
	v_cvt_pk_bf16_f32 v0, v0, s0
	global_store_short v[4:5], v0, off offset:1600
	v_mul_f32_e32 v3, 0xbfb8aa3b, v67
	v_exp_f32_e32 v3, v3
	v_rcp_f32_e32 v0, v2
	s_nop 0
	v_mul_f32_e32 v0, v66, v0
	v_add_f32_e32 v2, 1.0, v3
	v_mul_f32_e32 v0, v50, v0
	v_cvt_pk_bf16_f32 v0, v0, s0
	global_store_short v[6:7], v0, off offset:3136
	v_mul_f32_e32 v3, 0xbfb8aa3b, v68
	v_exp_f32_e32 v3, v3
	v_rcp_f32_e32 v0, v2
	s_nop 0
	v_mul_f32_e32 v0, v67, v0
	v_add_f32_e32 v2, 1.0, v3
	v_mul_f32_e32 v0, v51, v0
	v_cvt_pk_bf16_f32 v0, v0, s0
	global_store_short v[8:9], v0, off offset:64
	v_mul_f32_e32 v3, 0xbfb8aa3b, v69
	v_exp_f32_e32 v3, v3
	v_rcp_f32_e32 v0, v2
	s_nop 0
	v_mul_f32_e32 v0, v68, v0
	v_add_f32_e32 v2, 1.0, v3
	v_mul_f32_e32 v0, v52, v0
	v_cvt_pk_bf16_f32 v0, v0, s0
	global_store_short v[10:11], v0, off offset:64
	v_mul_f32_e32 v3, 0xbfb8aa3b, v70
	v_exp_f32_e32 v3, v3
	v_rcp_f32_e32 v0, v2
	s_nop 0
	v_mul_f32_e32 v0, v69, v0
	v_add_f32_e32 v2, 1.0, v3
	v_mul_f32_e32 v0, v53, v0
	v_cvt_pk_bf16_f32 v0, v0, s0
	global_store_short v[12:13], v0, off offset:1600
	v_mul_f32_e32 v3, 0xbfb8aa3b, v71
	v_exp_f32_e32 v3, v3
	v_rcp_f32_e32 v0, v2
	s_nop 0
	v_mul_f32_e32 v0, v70, v0
	v_add_f32_e32 v2, 1.0, v3
	v_mul_f32_e32 v0, v54, v0
	v_cvt_pk_bf16_f32 v0, v0, s0
	global_store_short v[14:15], v0, off offset:3136
	v_mul_f32_e32 v3, 0xbfb8aa3b, v72
	v_exp_f32_e32 v3, v3
	v_rcp_f32_e32 v0, v2
	s_nop 0
	v_mul_f32_e32 v0, v71, v0
	v_add_f32_e32 v2, 1.0, v3
	v_mul_f32_e32 v0, v55, v0
	v_cvt_pk_bf16_f32 v0, v0, s0
	global_store_short v[112:113], v0, off offset:64
	v_mul_f32_e32 v3, 0xbfb8aa3b, v73
	v_exp_f32_e32 v3, v3
	v_rcp_f32_e32 v0, v2
	s_nop 0
	v_mul_f32_e32 v0, v72, v0
	v_add_f32_e32 v2, 1.0, v3
	v_mul_f32_e32 v0, v56, v0
	v_cvt_pk_bf16_f32 v0, v0, s0
	global_store_short v[114:115], v0, off offset:64
	v_mul_f32_e32 v3, 0xbfb8aa3b, v74
	v_exp_f32_e32 v3, v3
	v_rcp_f32_e32 v0, v2
	s_nop 0
	v_mul_f32_e32 v0, v73, v0
	v_add_f32_e32 v2, 1.0, v3
	v_mul_f32_e32 v0, v57, v0
	v_cvt_pk_bf16_f32 v0, v0, s0
	global_store_short v[116:117], v0, off offset:1600
	v_mul_f32_e32 v3, 0xbfb8aa3b, v75
	v_exp_f32_e32 v3, v3
	v_rcp_f32_e32 v0, v2
	s_nop 0
	v_mul_f32_e32 v0, v74, v0
	v_add_f32_e32 v2, 1.0, v3
	v_mul_f32_e32 v0, v58, v0
	v_cvt_pk_bf16_f32 v0, v0, s0
	global_store_short v[118:119], v0, off offset:3136
	v_mul_f32_e32 v3, 0xbfb8aa3b, v76
	v_exp_f32_e32 v3, v3
	v_rcp_f32_e32 v0, v2
	s_nop 0
	v_mul_f32_e32 v0, v75, v0
	v_add_f32_e32 v2, 1.0, v3
	v_mul_f32_e32 v0, v59, v0
	v_cvt_pk_bf16_f32 v0, v0, s0
	global_store_short v[120:121], v0, off offset:64
	v_mul_f32_e32 v3, 0xbfb8aa3b, v77
	v_exp_f32_e32 v3, v3
	v_rcp_f32_e32 v0, v2
	s_nop 0
	v_mul_f32_e32 v0, v76, v0
	v_add_f32_e32 v2, 1.0, v3
	v_mul_f32_e32 v0, v60, v0
	v_cvt_pk_bf16_f32 v0, v0, s0
	global_store_short v[122:123], v0, off offset:64
	v_mul_f32_e32 v3, 0xbfb8aa3b, v78
	v_exp_f32_e32 v3, v3
	v_rcp_f32_e32 v0, v2
	s_nop 0
	v_mul_f32_e32 v0, v77, v0
	v_add_f32_e32 v2, 1.0, v3
	v_mul_f32_e32 v0, v61, v0
	v_cvt_pk_bf16_f32 v0, v0, s0
	global_store_short v[124:125], v0, off offset:1600
	v_mul_f32_e32 v3, 0xbfb8aa3b, v79
	v_exp_f32_e32 v3, v3
	v_rcp_f32_e32 v0, v2
	s_nop 0
	v_mul_f32_e32 v0, v78, v0
	v_add_f32_e32 v2, 1.0, v3
	v_mul_f32_e32 v0, v62, v0
	v_cvt_pk_bf16_f32 v0, v0, s0
	global_store_short v[128:129], v0, off offset:3136
	v_mul_f32_e32 v3, 0xbfb8aa3b, v16
	v_exp_f32_e32 v3, v3
	v_rcp_f32_e32 v0, v2
	s_nop 0
	v_mul_f32_e32 v0, v79, v0
	v_add_f32_e32 v2, 1.0, v3
	v_mul_f32_e32 v0, v63, v0
	v_cvt_pk_bf16_f32 v0, v0, s0
	global_store_short v[126:127], v0, off offset:64
	v_mul_f32_e32 v3, 0xbfb8aa3b, v17
	v_exp_f32_e32 v3, v3
	v_rcp_f32_e32 v0, v2
	s_nop 0
	v_mul_f32_e32 v0, v16, v0
	v_add_f32_e32 v2, 1.0, v3
	v_mul_f32_e32 v0, v32, v0
	v_cvt_pk_bf16_f32 v0, v0, s0
	global_store_short v[130:131], v0, off offset:64
	v_mul_f32_e32 v3, 0xbfb8aa3b, v18
	v_exp_f32_e32 v3, v3
	v_rcp_f32_e32 v0, v2
	s_nop 0
	v_mul_f32_e32 v0, v17, v0
	v_add_f32_e32 v2, 1.0, v3
	v_mul_f32_e32 v0, v33, v0
	v_cvt_pk_bf16_f32 v0, v0, s0
	global_store_short v[80:81], v0, off offset:1600
	v_mul_f32_e32 v3, 0xbfb8aa3b, v19
	v_exp_f32_e32 v3, v3
	v_rcp_f32_e32 v0, v2
	s_nop 0
	v_mul_f32_e32 v0, v18, v0
	v_add_f32_e32 v2, 1.0, v3
	v_mul_f32_e32 v0, v34, v0
	v_cvt_pk_bf16_f32 v0, v0, s0
	global_store_short v[96:97], v0, off offset:3136
	v_mul_f32_e32 v3, 0xbfb8aa3b, v20
	v_exp_f32_e32 v3, v3
	v_rcp_f32_e32 v0, v2
	s_nop 0
	v_mul_f32_e32 v0, v19, v0
	v_add_f32_e32 v2, 1.0, v3
	v_mul_f32_e32 v0, v35, v0
	v_cvt_pk_bf16_f32 v0, v0, s0
	global_store_short v[82:83], v0, off offset:64
	v_mul_f32_e32 v3, 0xbfb8aa3b, v21
	v_exp_f32_e32 v3, v3
	v_rcp_f32_e32 v0, v2
	s_nop 0
	v_mul_f32_e32 v0, v20, v0
	v_add_f32_e32 v2, 1.0, v3
	v_mul_f32_e32 v0, v36, v0
	v_cvt_pk_bf16_f32 v0, v0, s0
	global_store_short v[98:99], v0, off offset:64
	v_mul_f32_e32 v3, 0xbfb8aa3b, v22
	v_exp_f32_e32 v3, v3
	v_rcp_f32_e32 v0, v2
	s_nop 0
	v_mul_f32_e32 v0, v21, v0
	v_add_f32_e32 v2, 1.0, v3
	v_mul_f32_e32 v0, v37, v0
	v_cvt_pk_bf16_f32 v0, v0, s0
	global_store_short v[84:85], v0, off offset:1600
	v_mul_f32_e32 v3, 0xbfb8aa3b, v23
	v_exp_f32_e32 v3, v3
	v_rcp_f32_e32 v0, v2
	s_nop 0
	v_mul_f32_e32 v0, v22, v0
	v_add_f32_e32 v2, 1.0, v3
	v_mul_f32_e32 v0, v38, v0
	v_cvt_pk_bf16_f32 v0, v0, s0
	global_store_short v[100:101], v0, off offset:3136
	v_mul_f32_e32 v3, 0xbfb8aa3b, v24
	v_exp_f32_e32 v3, v3
	v_rcp_f32_e32 v0, v2
	s_nop 0
	v_mul_f32_e32 v0, v23, v0
	v_add_f32_e32 v2, 1.0, v3
	v_mul_f32_e32 v0, v39, v0
	v_cvt_pk_bf16_f32 v0, v0, s0
	global_store_short v[86:87], v0, off offset:64
	v_mul_f32_e32 v3, 0xbfb8aa3b, v25
	v_exp_f32_e32 v3, v3
	v_rcp_f32_e32 v0, v2
	s_nop 0
	v_mul_f32_e32 v0, v24, v0
	v_add_f32_e32 v2, 1.0, v3
	v_mul_f32_e32 v0, v40, v0
	v_cvt_pk_bf16_f32 v0, v0, s0
	global_store_short v[102:103], v0, off offset:64
	v_mul_f32_e32 v3, 0xbfb8aa3b, v26
	v_exp_f32_e32 v3, v3
	v_rcp_f32_e32 v0, v2
	s_nop 0
	v_mul_f32_e32 v0, v25, v0
	v_add_f32_e32 v2, 1.0, v3
	v_mul_f32_e32 v0, v41, v0
	v_cvt_pk_bf16_f32 v0, v0, s0
	global_store_short v[88:89], v0, off offset:1600
	v_mul_f32_e32 v3, 0xbfb8aa3b, v27
	v_exp_f32_e32 v3, v3
	v_rcp_f32_e32 v0, v2
	s_nop 0
	v_mul_f32_e32 v0, v26, v0
	v_add_f32_e32 v2, 1.0, v3
	v_mul_f32_e32 v0, v42, v0
	v_cvt_pk_bf16_f32 v0, v0, s0
	global_store_short v[104:105], v0, off offset:3136
	v_mul_f32_e32 v3, 0xbfb8aa3b, v28
	v_exp_f32_e32 v3, v3
	v_rcp_f32_e32 v0, v2
	s_nop 0
	v_mul_f32_e32 v0, v27, v0
	v_add_f32_e32 v2, 1.0, v3
	v_mul_f32_e32 v0, v43, v0
	v_cvt_pk_bf16_f32 v0, v0, s0
	global_store_short v[90:91], v0, off offset:64
	v_mul_f32_e32 v3, 0xbfb8aa3b, v29
	v_exp_f32_e32 v3, v3
	v_rcp_f32_e32 v0, v2
	s_nop 0
	v_mul_f32_e32 v0, v28, v0
	v_add_f32_e32 v2, 1.0, v3
	v_mul_f32_e32 v0, v44, v0
	v_cvt_pk_bf16_f32 v0, v0, s0
	global_store_short v[106:107], v0, off offset:64
	v_mul_f32_e32 v3, 0xbfb8aa3b, v30
	v_exp_f32_e32 v3, v3
	v_rcp_f32_e32 v0, v2
	s_nop 0
	v_mul_f32_e32 v0, v29, v0
	v_add_f32_e32 v2, 1.0, v3
	v_mul_f32_e32 v0, v45, v0
	v_cvt_pk_bf16_f32 v0, v0, s0
	global_store_short v[92:93], v0, off offset:1600
	v_mul_f32_e32 v3, 0xbfb8aa3b, v31
	v_exp_f32_e32 v3, v3
	v_rcp_f32_e32 v0, v2
	s_nop 0
	v_mul_f32_e32 v0, v30, v0
	v_add_f32_e32 v2, 1.0, v3
	v_mul_f32_e32 v0, v46, v0
	v_cvt_pk_bf16_f32 v0, v0, s0
	global_store_short v[108:109], v0, off offset:3136
	v_rcp_f32_e32 v0, v2
	s_nop 0
	v_mul_f32_e32 v0, v31, v0
	v_mul_f32_e32 v0, v47, v0
	v_cvt_pk_bf16_f32 v0, v0, s0
	global_store_short v[94:95], v0, off offset:64
	s_cbranch_scc0 .LBB0_941

.LBB0_954:
	s_ashr_i32 s0, s23, 31
	s_lshr_b32 s0, s0, 27
	s_add_i32 s20, s23, s0
	s_and_b32 s0, s20, 0xffffffe0
	s_sub_i32 s26, s23, s0
	s_mul_i32 s0, s26, 0xb0000
	s_ashr_i32 s1, s0, 31
	s_lshl_b32 s20, s20, 2
	s_and_b32 s27, s20, 0xffffff80
	s_lshl_b64 s[0:1], s[0:1], 1
	v_readlane_b32 s4, v254, 21
	v_readlane_b32 s5, v254, 22
	s_add_u32 s0, s4, s0
	s_addc_u32 s1, s5, s1
	s_mul_i32 s20, s27, 0x1600
	s_mul_hi_i32 s21, s27, 0x1600
	s_add_u32 s20, s24, s20
	s_addc_u32 s21, s25, s21
	s_waitcnt lgkmcnt(0)
	v_lshlrev_b32_e32 v142, 1, v133
	v_lshrrev_b32_e32 v140, 3, v196
	v_lshrrev_b32_e32 v141, 4, v196
	v_xor_b32_e32 v141, v141, v196
	v_and_b32_e32 v141, 7, v141
	v_lshlrev_b32_e32 v141, 4, v141
	v_mul_u32_u24_e32 v140, 0x1600, v140
	v_add_u32_e32 v82, v140, v141
	v_add_u32_e32 v83, 0x58000, v82
	v_add_u32_e32 v84, 0xb0000, v82
	v_add_u32_e32 v85, 0x108000, v82
	v_add_u32_e32 v140, 0, v130
	v_xor_b32_e32 v140, v140, v131
	v_lshlrev_b32_e32 v140, 4, v140
	v_add3_u32 v86, v134, v140, 16
	v_add3_u32 v136, v142, v140, 16
	v_add_u32_e32 v140, 2, v130
	v_xor_b32_e32 v140, v140, v131
	v_lshlrev_b32_e32 v140, 4, v140
	v_add3_u32 v87, v134, v140, 16
	v_add3_u32 v137, v142, v140, 16
	v_add_u32_e32 v140, 4, v130
	v_xor_b32_e32 v140, v140, v131
	v_lshlrev_b32_e32 v140, 4, v140
	v_add3_u32 v88, v134, v140, 16
	v_add3_u32 v138, v142, v140, 16
	v_add_u32_e32 v140, 6, v130
	v_xor_b32_e32 v140, v140, v131
	v_lshlrev_b32_e32 v140, 4, v140
	v_add3_u32 v89, v134, v140, 16
	v_add3_u32 v139, v142, v140, 16
	v_lshrrev_b32_e32 v140, 6, v196
	v_mov_b64_e32 v[2:3], 0
	v_mov_b64_e32 v[4:5], 0
	v_mov_b64_e32 v[6:7], 0
	v_mov_b64_e32 v[8:9], 0
	v_mov_b64_e32 v[10:11], 0
	v_mov_b64_e32 v[12:13], 0
	v_mov_b64_e32 v[14:15], 0
	v_mov_b64_e32 v[16:17], 0
	v_mov_b64_e32 v[18:19], 0
	v_mov_b64_e32 v[20:21], 0
	v_mov_b64_e32 v[22:23], 0
	v_mov_b64_e32 v[24:25], 0
	v_mov_b64_e32 v[26:27], 0
	v_mov_b64_e32 v[28:29], 0
	v_mov_b64_e32 v[30:31], 0
	v_mov_b64_e32 v[32:33], 0
	v_mov_b64_e32 v[34:35], 0
	v_mov_b64_e32 v[36:37], 0
	v_mov_b64_e32 v[38:39], 0
	v_mov_b64_e32 v[40:41], 0
	v_mov_b64_e32 v[42:43], 0
	v_mov_b64_e32 v[44:45], 0
	v_mov_b64_e32 v[46:47], 0
	v_mov_b64_e32 v[48:49], 0
	v_mov_b64_e32 v[50:51], 0
	v_mov_b64_e32 v[52:53], 0
	v_mov_b64_e32 v[54:55], 0
	v_mov_b64_e32 v[56:57], 0
	v_mov_b64_e32 v[58:59], 0
	v_mov_b64_e32 v[60:61], 0
	v_mov_b64_e32 v[62:63], 0
	v_mov_b64_e32 v[64:65], 0
	v_readfirstlane_b32 s43, v140
	s_lshl_b32 s43, s43, 10
	s_add_i32 s43, s43, 16
	s_add_i32 vcc_hi, s43, 0xc000
	s_mov_b32 m0, s43
	s_nop 0
	global_load_lds_dwordx4 v82, s[0:1]
	s_add_u32 m0, m0, 0x2000
	s_nop 0
	global_load_lds_dwordx4 v83, s[0:1]
	s_add_u32 m0, m0, 0x2000
	s_nop 0
	global_load_lds_dwordx4 v84, s[0:1]
	s_add_u32 m0, m0, 0x2000
	s_nop 0
	global_load_lds_dwordx4 v85, s[0:1]
	s_add_u32 m0, m0, 0x2000
	s_nop 0
	global_load_lds_dwordx4 v82, s[20:21]
	s_add_u32 m0, m0, 0x2000
	s_nop 0
	global_load_lds_dwordx4 v83, s[20:21]
	s_add_u32 s0, s0, 0x80
	s_addc_u32 s1, s1, 0
	s_add_u32 s20, s20, 0x80
	s_addc_u32 s21, s21, 0
	s_mov_b32 m0, vcc_hi
	s_nop 0
	global_load_lds_dwordx4 v82, s[0:1]
	s_add_u32 m0, m0, 0x2000
	s_nop 0
	global_load_lds_dwordx4 v83, s[0:1]
	s_add_u32 m0, m0, 0x2000
	s_nop 0
	global_load_lds_dwordx4 v84, s[0:1]
	s_add_u32 m0, m0, 0x2000
	s_nop 0
	global_load_lds_dwordx4 v85, s[0:1]
	s_add_u32 m0, m0, 0x2000
	s_nop 0
	global_load_lds_dwordx4 v82, s[20:21]
	s_add_u32 m0, m0, 0x2000
	s_nop 0
	global_load_lds_dwordx4 v83, s[20:21]
	s_add_u32 s0, s0, 0x80
	s_addc_u32 s1, s1, 0
	s_add_u32 s20, s20, 0x80
	s_addc_u32 s21, s21, 0
	s_mov_b32 s41, 0
	s_movk_i32 s40, 42
.Lw2_loop:
	s_waitcnt vmcnt(6)
	s_barrier
	s_add_i32 vcc_hi, s41, 2
	s_cmp_ge_u32 vcc_hi, 3
	s_cselect_b32 vcc_lo, 3, 0
	s_sub_i32 vcc_hi, vcc_hi, vcc_lo
	s_mul_i32 vcc_hi, vcc_hi, 0xc000
	s_add_i32 vcc_hi, vcc_hi, s43
	ds_read_b128 v[144:147], v86
	ds_read_b128 v[148:151], v86 offset:4096
	ds_read_b128 v[152:155], v136 offset:32768
	ds_read_b128 v[156:159], v136 offset:36864
	ds_read_b128 v[66:69], v87
	ds_read_b128 v[70:73], v87 offset:4096
	ds_read_b128 v[74:77], v137 offset:32768
	ds_read_b128 v[78:81], v137 offset:36864
	s_waitcnt lgkmcnt(4)
	s_setprio 1
	v_mfma_f32_32x32x16_bf16 v[50:65], v[144:147], v[152:155], v[50:65]
	s_mov_b32 m0, vcc_hi
	v_mfma_f32_32x32x16_bf16 v[18:33], v[148:151], v[152:155], v[18:33]
	global_load_lds_dwordx4 v82, s[0:1]
	s_add_u32 m0, m0, 0x2000
	v_mfma_f32_32x32x16_bf16 v[34:49], v[144:147], v[156:159], v[34:49]
	global_load_lds_dwordx4 v83, s[0:1]
	s_add_u32 m0, m0, 0x2000
	v_mfma_f32_32x32x16_bf16 v[2:17], v[148:151], v[156:159], v[2:17]
	global_load_lds_dwordx4 v84, s[0:1]
	s_add_u32 m0, m0, 0x2000
	s_nop 0
	global_load_lds_dwordx4 v85, s[0:1]
	s_add_u32 m0, m0, 0x2000
	s_nop 0
	global_load_lds_dwordx4 v82, s[20:21]
	s_add_u32 m0, m0, 0x2000
	s_nop 0
	global_load_lds_dwordx4 v83, s[20:21]
	s_add_u32 s0, s0, 0x80
	s_addc_u32 s1, s1, 0
	s_add_u32 s20, s20, 0x80
	s_addc_u32 s21, s21, 0
	s_setprio 0
	ds_read_b128 v[144:147], v88
	ds_read_b128 v[148:151], v88 offset:4096
	ds_read_b128 v[152:155], v138 offset:32768
	ds_read_b128 v[156:159], v138 offset:36864
	s_waitcnt lgkmcnt(4)
	s_setprio 1
	v_mfma_f32_32x32x16_bf16 v[50:65], v[66:69], v[74:77], v[50:65]
	v_mfma_f32_32x32x16_bf16 v[18:33], v[70:73], v[74:77], v[18:33]
	v_mfma_f32_32x32x16_bf16 v[34:49], v[66:69], v[78:81], v[34:49]
	v_mfma_f32_32x32x16_bf16 v[2:17], v[70:73], v[78:81], v[2:17]
	s_setprio 0
	ds_read_b128 v[66:69], v89
	ds_read_b128 v[70:73], v89 offset:4096
	ds_read_b128 v[74:77], v139 offset:32768
	ds_read_b128 v[78:81], v139 offset:36864
	s_waitcnt lgkmcnt(4)
	s_setprio 1
	v_mfma_f32_32x32x16_bf16 v[50:65], v[144:147], v[152:155], v[50:65]
	v_mfma_f32_32x32x16_bf16 v[18:33], v[148:151], v[152:155], v[18:33]
	v_mfma_f32_32x32x16_bf16 v[34:49], v[144:147], v[156:159], v[34:49]
	v_mfma_f32_32x32x16_bf16 v[2:17], v[148:151], v[156:159], v[2:17]
	s_setprio 0
	s_waitcnt lgkmcnt(0)
	s_setprio 1
	v_mfma_f32_32x32x16_bf16 v[50:65], v[66:69], v[74:77], v[50:65]
	v_mfma_f32_32x32x16_bf16 v[18:33], v[70:73], v[74:77], v[18:33]
	v_mfma_f32_32x32x16_bf16 v[34:49], v[66:69], v[78:81], v[34:49]
	v_mfma_f32_32x32x16_bf16 v[2:17], v[70:73], v[78:81], v[2:17]
	s_setprio 0
	s_add_i32 s41, s41, 1
	s_cmp_eq_u32 s41, 3
	s_cselect_b32 vcc_lo, 0xfffdc000, 0
	s_cselect_b32 s41, 0, s41
	s_add_i32 vcc_lo, vcc_lo, 0xc000
	v_add_u32_e32 v86, vcc_lo, v86
	v_add_u32_e32 v136, vcc_lo, v136
	v_add_u32_e32 v87, vcc_lo, v87
	v_add_u32_e32 v137, vcc_lo, v137
	v_add_u32_e32 v88, vcc_lo, v88
	v_add_u32_e32 v138, vcc_lo, v138
	v_add_u32_e32 v89, vcc_lo, v89
	v_add_u32_e32 v139, vcc_lo, v139
	s_add_i32 s40, s40, -1
	s_cmp_lg_u32 s40, 0
	s_cbranch_scc1 .Lw2_loop
	s_waitcnt vmcnt(6)
	s_barrier
	ds_read_b128 v[144:147], v86
	ds_read_b128 v[148:151], v86 offset:4096
	ds_read_b128 v[152:155], v136 offset:32768
	ds_read_b128 v[156:159], v136 offset:36864
	ds_read_b128 v[66:69], v87
	ds_read_b128 v[70:73], v87 offset:4096
	ds_read_b128 v[74:77], v137 offset:32768
	ds_read_b128 v[78:81], v137 offset:36864
	s_waitcnt lgkmcnt(4)
	s_setprio 1
	v_mfma_f32_32x32x16_bf16 v[50:65], v[144:147], v[152:155], v[50:65]
	v_mfma_f32_32x32x16_bf16 v[18:33], v[148:151], v[152:155], v[18:33]
	v_mfma_f32_32x32x16_bf16 v[34:49], v[144:147], v[156:159], v[34:49]
	v_mfma_f32_32x32x16_bf16 v[2:17], v[148:151], v[156:159], v[2:17]
	s_setprio 0
	ds_read_b128 v[144:147], v88
	ds_read_b128 v[148:151], v88 offset:4096
	ds_read_b128 v[152:155], v138 offset:32768
	ds_read_b128 v[156:159], v138 offset:36864
	s_waitcnt lgkmcnt(4)
	s_setprio 1
	v_mfma_f32_32x32x16_bf16 v[50:65], v[66:69], v[74:77], v[50:65]
	v_mfma_f32_32x32x16_bf16 v[18:33], v[70:73], v[74:77], v[18:33]
	v_mfma_f32_32x32x16_bf16 v[34:49], v[66:69], v[78:81], v[34:49]
	v_mfma_f32_32x32x16_bf16 v[2:17], v[70:73], v[78:81], v[2:17]
	s_setprio 0
	ds_read_b128 v[66:69], v89
	ds_read_b128 v[70:73], v89 offset:4096
	ds_read_b128 v[74:77], v139 offset:32768
	ds_read_b128 v[78:81], v139 offset:36864
	s_waitcnt lgkmcnt(4)
	s_setprio 1
	v_mfma_f32_32x32x16_bf16 v[50:65], v[144:147], v[152:155], v[50:65]
	v_mfma_f32_32x32x16_bf16 v[18:33], v[148:151], v[152:155], v[18:33]
	v_mfma_f32_32x32x16_bf16 v[34:49], v[144:147], v[156:159], v[34:49]
	v_mfma_f32_32x32x16_bf16 v[2:17], v[148:151], v[156:159], v[2:17]
	s_setprio 0
	s_waitcnt lgkmcnt(0)
	s_setprio 1
	v_mfma_f32_32x32x16_bf16 v[50:65], v[66:69], v[74:77], v[50:65]
	v_mfma_f32_32x32x16_bf16 v[18:33], v[70:73], v[74:77], v[18:33]
	v_mfma_f32_32x32x16_bf16 v[34:49], v[66:69], v[78:81], v[34:49]
	v_mfma_f32_32x32x16_bf16 v[2:17], v[70:73], v[78:81], v[2:17]
	s_setprio 0
	s_add_i32 s41, s41, 1
	s_cmp_eq_u32 s41, 3
	s_cselect_b32 vcc_lo, 0xfffdc000, 0
	s_cselect_b32 s41, 0, s41
	s_add_i32 vcc_lo, vcc_lo, 0xc000
	v_add_u32_e32 v86, vcc_lo, v86
	v_add_u32_e32 v136, vcc_lo, v136
	v_add_u32_e32 v87, vcc_lo, v87
	v_add_u32_e32 v137, vcc_lo, v137
	v_add_u32_e32 v88, vcc_lo, v88
	v_add_u32_e32 v138, vcc_lo, v138
	v_add_u32_e32 v89, vcc_lo, v89
	v_add_u32_e32 v139, vcc_lo, v139
	s_waitcnt vmcnt(0)
	s_barrier
	ds_read_b128 v[144:147], v86
	ds_read_b128 v[148:151], v86 offset:4096
	ds_read_b128 v[152:155], v136 offset:32768
	ds_read_b128 v[156:159], v136 offset:36864
	ds_read_b128 v[66:69], v87
	ds_read_b128 v[70:73], v87 offset:4096
	ds_read_b128 v[74:77], v137 offset:32768
	ds_read_b128 v[78:81], v137 offset:36864
	s_waitcnt lgkmcnt(4)
	s_setprio 1
	v_mfma_f32_32x32x16_bf16 v[50:65], v[144:147], v[152:155], v[50:65]
	v_mfma_f32_32x32x16_bf16 v[18:33], v[148:151], v[152:155], v[18:33]
	v_mfma_f32_32x32x16_bf16 v[34:49], v[144:147], v[156:159], v[34:49]
	v_mfma_f32_32x32x16_bf16 v[2:17], v[148:151], v[156:159], v[2:17]
	s_setprio 0
	ds_read_b128 v[144:147], v88
	ds_read_b128 v[148:151], v88 offset:4096
	ds_read_b128 v[152:155], v138 offset:32768
	ds_read_b128 v[156:159], v138 offset:36864
	s_waitcnt lgkmcnt(4)
	s_setprio 1
	v_mfma_f32_32x32x16_bf16 v[50:65], v[66:69], v[74:77], v[50:65]
	v_mfma_f32_32x32x16_bf16 v[18:33], v[70:73], v[74:77], v[18:33]
	v_mfma_f32_32x32x16_bf16 v[34:49], v[66:69], v[78:81], v[34:49]
	v_mfma_f32_32x32x16_bf16 v[2:17], v[70:73], v[78:81], v[2:17]
	s_setprio 0
	ds_read_b128 v[66:69], v89
	ds_read_b128 v[70:73], v89 offset:4096
	ds_read_b128 v[74:77], v139 offset:32768
	ds_read_b128 v[78:81], v139 offset:36864
	s_waitcnt lgkmcnt(4)
	s_setprio 1
	v_mfma_f32_32x32x16_bf16 v[50:65], v[144:147], v[152:155], v[50:65]
	v_mfma_f32_32x32x16_bf16 v[18:33], v[148:151], v[152:155], v[18:33]
	v_mfma_f32_32x32x16_bf16 v[34:49], v[144:147], v[156:159], v[34:49]
	v_mfma_f32_32x32x16_bf16 v[2:17], v[148:151], v[156:159], v[2:17]
	s_setprio 0
	s_waitcnt lgkmcnt(0)
	s_setprio 1
	v_mfma_f32_32x32x16_bf16 v[50:65], v[66:69], v[74:77], v[50:65]
	v_mfma_f32_32x32x16_bf16 v[18:33], v[70:73], v[74:77], v[18:33]
	v_mfma_f32_32x32x16_bf16 v[34:49], v[66:69], v[78:81], v[34:49]
	v_mfma_f32_32x32x16_bf16 v[2:17], v[70:73], v[78:81], v[2:17]
	s_setprio 0
	s_barrier
	v_mov_b32_e32 v0, v1
	s_nop 7
	s_waitcnt vmcnt(5)
	v_lshl_add_u32 v68, s26, 8, v132
	v_add_u32_e32 v0, 0xfffff000, v68
	v_lshrrev_b32_e32 v0, 11, v0
	s_movk_i32 s0, 0x1800
	v_mad_u32_u24 v0, v0, s0, s0
	v_cmp_lt_i32_e32 vcc, s50, v68
	v_ashrrev_i32_e32 v69, 31, v68
	v_readlane_b32 s4, v254, 0
	v_or_b32_e32 v66, s27, v135
	v_cndmask_b32_e32 v160, 0, v0, vcc
	s_waitcnt vmcnt(4)
	v_lshlrev_b64 v[70:71], 12, v[68:69]
	v_readlane_b32 s5, v254, 1
	v_ashrrev_i32_e32 v67, 31, v66
	v_mov_b32_e32 v95, v1
	v_lshl_add_u64 v[72:73], s[4:5], 0, v[70:71]
	v_add_u32_e32 v70, v160, v66
	v_ashrrev_i32_e32 v71, 31, v70
	v_lshl_add_u64 v[70:71], v[70:71], 2, s[28:29]
	global_load_dword v69, v[70:71], off
	v_lshlrev_b64 v[70:71], 2, v[66:67]
	s_waitcnt vmcnt(4)
	v_lshl_add_u64 v[74:75], v[72:73], 0, v[70:71]
	v_mov_b32_e32 v109, v1
	v_mov_b32_e32 v111, v1
	v_lshl_add_u64 v[72:73], v[74:75], 0, v[94:95]
	v_mov_b32_e32 v97, v1
	v_mov_b32_e32 v99, v1
	v_mov_b32_e32 v101, v1
	v_mov_b32_e32 v103, v1
	v_mov_b32_e32 v105, v1
	v_mov_b32_e32 v107, v1
	s_waitcnt vmcnt(1)
	v_lshl_add_u64 v[88:89], v[74:75], 0, v[108:109]
	v_lshl_add_u64 v[144:145], v[74:75], 0, v[110:111]
	v_mov_b32_e32 v113, v1
	v_lshl_add_u64 v[76:77], v[74:75], 0, v[96:97]
	v_lshl_add_u64 v[78:79], v[74:75], 0, v[98:99]
	v_lshl_add_u64 v[80:81], v[74:75], 0, v[100:101]
	v_lshl_add_u64 v[82:83], v[74:75], 0, v[102:103]
	v_lshl_add_u64 v[84:85], v[74:75], 0, v[104:105]
	v_lshl_add_u64 v[86:87], v[74:75], 0, v[106:107]
	global_load_dword v67, v[72:73], off
	global_load_dword v161, v[76:77], off
	global_load_dword v162, v[78:79], off
	global_load_dword v163, v[80:81], off
	global_load_dword v164, v[82:83], off
	global_load_dword v165, v[84:85], off
	global_load_dword v166, v[86:87], off
	global_load_dword v167, v[88:89], off
	global_load_dword v168, v[144:145], off
	v_lshl_add_u64 v[146:147], v[74:75], 0, v[112:113]
	v_mov_b32_e32 v115, v1
	global_load_dword v169, v[146:147], off
	v_lshl_add_u64 v[148:149], v[74:75], 0, v[114:115]
	v_mov_b32_e32 v117, v1
	global_load_dword v170, v[148:149], off
	v_lshl_add_u64 v[150:151], v[74:75], 0, v[116:117]
	v_mov_b32_e32 v119, v1
	global_load_dword v171, v[150:151], off
	v_lshl_add_u64 v[152:153], v[74:75], 0, v[118:119]
	v_mov_b32_e32 v121, v1
	global_load_dword v172, v[152:153], off
	v_lshl_add_u64 v[154:155], v[74:75], 0, v[120:121]
	v_mov_b32_e32 v123, v1
	global_load_dword v173, v[154:155], off
	global_load_dword v177, v[72:73], off offset:128
	v_lshl_add_u64 v[156:157], v[74:75], 0, v[122:123]
	v_mov_b32_e32 v125, v1
	global_load_dword v174, v[156:157], off
	v_lshl_add_u64 v[158:159], v[74:75], 0, v[124:125]
	global_load_dword v175, v[158:159], off
	v_add_f32_e32 v50, 0, v50
	v_add_f32_e32 v51, 0, v51
	v_add_f32_e32 v52, 0, v52
	v_add_f32_e32 v53, 0, v53
	v_add_f32_e32 v54, 0, v54
	v_add_f32_e32 v55, 0, v55
	v_add_f32_e32 v56, 0, v56
	v_add_f32_e32 v57, 0, v57
	v_or_b32_e32 v176, 32, v66
	s_mov_b64 s[0:1], 0x80
	v_add_f32_e32 v34, 0, v34
	v_add_f32_e32 v35, 0, v35
	v_add_f32_e32 v36, 0, v36
	v_add_f32_e32 v37, 0, v37
	v_add_f32_e32 v41, 0, v41
	v_add_f32_e32 v38, 0, v38
	v_add_f32_e32 v39, 0, v39
	v_add_f32_e32 v40, 0, v40
	v_add_f32_e32 v18, 0, v18
	v_add_f32_e32 v19, 0, v19
	v_add_f32_e32 v20, 0, v20
	v_add_f32_e32 v21, 0, v21
	v_add_f32_e32 v2, 0, v2
	s_add_i32 s23, s23, s22
	v_add_f32_e32 v3, 0, v3
	v_add_f32_e32 v4, 0, v4
	v_add_f32_e32 v5, 0, v5
	s_cmpk_gt_i32 s23, 0xff
	v_readlane_b32 s6, v254, 2
	v_readlane_b32 s7, v254, 3
	v_readlane_b32 s8, v254, 4
	v_readlane_b32 s9, v254, 5
	v_readlane_b32 s10, v254, 6
	v_readlane_b32 s11, v254, 7
	v_readlane_b32 s12, v254, 8
	v_readlane_b32 s13, v254, 9
	v_readlane_b32 s14, v254, 10
	v_readlane_b32 s15, v254, 11
	v_readlane_b32 s16, v254, 12
	v_readlane_b32 s17, v254, 13
	v_readlane_b32 s18, v254, 14
	v_readlane_b32 s19, v254, 15
	s_waitcnt vmcnt(16)
	v_fmac_f32_e32 v67, v50, v69
	v_add_f32_e32 v50, 0, v58
	s_waitcnt vmcnt(15)
	v_fmac_f32_e32 v161, v51, v69
	s_waitcnt vmcnt(14)
	v_fmac_f32_e32 v162, v52, v69
	s_waitcnt vmcnt(13)
	v_fmac_f32_e32 v163, v53, v69
	s_waitcnt vmcnt(12)
	v_fmac_f32_e32 v164, v54, v69
	s_waitcnt vmcnt(11)
	v_fmac_f32_e32 v165, v55, v69
	s_waitcnt vmcnt(10)
	v_fmac_f32_e32 v166, v56, v69
	s_waitcnt vmcnt(8)
	v_fmac_f32_e32 v168, v50, v69
	v_add_f32_e32 v50, 0, v59
	v_fmac_f32_e32 v167, v57, v69
	s_waitcnt vmcnt(7)
	v_fmac_f32_e32 v169, v50, v69
	v_add_f32_e32 v50, 0, v60
	global_store_dword v[72:73], v67, off
	global_store_dword v[76:77], v161, off
	global_store_dword v[78:79], v162, off
	global_store_dword v[80:81], v163, off
	global_store_dword v[82:83], v164, off
	global_store_dword v[84:85], v165, off
	global_store_dword v[86:87], v166, off
	global_store_dword v[88:89], v167, off
	s_waitcnt vmcnt(14)
	v_fmac_f32_e32 v170, v50, v69
	v_add_f32_e32 v50, 0, v61
	v_add_f32_e32 v67, 0, v65
	s_waitcnt vmcnt(13)
	v_fmac_f32_e32 v171, v50, v69
	v_add_f32_e32 v50, 0, v62
	global_store_dword v[144:145], v168, off
	s_waitcnt vmcnt(13)
	v_fmac_f32_e32 v172, v50, v69
	v_add_f32_e32 v50, 0, v63
	global_store_dword v[146:147], v169, off
	s_waitcnt vmcnt(13)
	v_fmac_f32_e32 v173, v50, v69
	v_add_f32_e32 v50, 0, v64
	global_store_dword v[148:149], v170, off
	global_store_dword v[150:151], v171, off
	s_waitcnt vmcnt(13)
	v_fmac_f32_e32 v174, v50, v69
	v_lshl_add_u64 v[50:51], v[74:75], 0, s[0:1]
	v_add_u32_e32 v74, v160, v176
	global_store_dword v[152:153], v172, off
	global_store_dword v[154:155], v173, off
	global_store_dword v[156:157], v174, off
	v_lshl_add_u64 v[52:53], v[50:51], 0, v[96:97]
	s_waitcnt vmcnt(15)
	v_fmac_f32_e32 v175, v67, v69
	v_ashrrev_i32_e32 v75, 31, v74
	v_lshl_add_u64 v[54:55], v[50:51], 0, v[98:99]
	v_lshl_add_u64 v[56:57], v[50:51], 0, v[100:101]
	v_lshl_add_u64 v[58:59], v[50:51], 0, v[102:103]
	v_lshl_add_u64 v[60:61], v[50:51], 0, v[104:105]
	v_lshl_add_u64 v[62:63], v[50:51], 0, v[106:107]
	v_lshl_add_u64 v[64:65], v[50:51], 0, v[108:109]
	global_load_dword v88, v[52:53], off
	global_load_dword v89, v[54:55], off
	global_load_dword v144, v[56:57], off
	global_load_dword v145, v[58:59], off
	global_load_dword v146, v[60:61], off
	global_load_dword v147, v[62:63], off
	global_load_dword v148, v[64:65], off
	v_lshl_add_u64 v[74:75], v[74:75], 2, s[28:29]
	global_store_dword v[158:159], v175, off
	global_load_dword v67, v[74:75], off
	v_lshl_add_u64 v[74:75], v[50:51], 0, v[110:111]
	global_load_dword v69, v[74:75], off
	v_lshl_add_u64 v[76:77], v[50:51], 0, v[112:113]
	global_load_dword v149, v[76:77], off
	v_lshl_add_u64 v[78:79], v[50:51], 0, v[114:115]
	global_load_dword v150, v[78:79], off
	v_lshl_add_u64 v[80:81], v[50:51], 0, v[116:117]
	global_load_dword v151, v[80:81], off
	v_lshl_add_u64 v[82:83], v[50:51], 0, v[118:119]
	global_load_dword v152, v[82:83], off
	v_lshl_add_u64 v[84:85], v[50:51], 0, v[120:121]
	global_load_dword v153, v[84:85], off
	v_lshl_add_u64 v[86:87], v[50:51], 0, v[122:123]
	global_load_dword v154, v[86:87], off
	v_lshl_add_u64 v[50:51], v[50:51], 0, v[124:125]
	global_load_dword v155, v[50:51], off
	s_waitcnt vmcnt(8)
	v_fmac_f32_e32 v177, v34, v67
	v_add_f32_e32 v34, 0, v42
	s_waitcnt vmcnt(7)
	v_fmac_f32_e32 v69, v34, v67
	v_add_f32_e32 v34, 0, v43
	s_waitcnt vmcnt(6)
	v_fmac_f32_e32 v149, v34, v67
	v_add_f32_e32 v34, 0, v44
	s_waitcnt vmcnt(5)
	v_fmac_f32_e32 v150, v34, v67
	v_add_f32_e32 v34, 0, v45
	s_waitcnt vmcnt(4)
	v_fmac_f32_e32 v151, v34, v67
	v_add_f32_e32 v34, 0, v46
	s_waitcnt vmcnt(3)
	v_fmac_f32_e32 v152, v34, v67
	v_add_f32_e32 v34, 0, v47
	s_waitcnt vmcnt(2)
	v_fmac_f32_e32 v153, v34, v67
	v_add_f32_e32 v34, 0, v48
	s_waitcnt vmcnt(1)
	v_fmac_f32_e32 v154, v34, v67
	v_add_f32_e32 v34, 0, v49
	s_waitcnt vmcnt(0)
	v_fmac_f32_e32 v155, v34, v67
	v_or_b32_e32 v34, 32, v68
	v_cmp_lt_i32_e32 vcc, s50, v34
	v_fmac_f32_e32 v88, v35, v67
	v_ashrrev_i32_e32 v35, 31, v34
	v_cndmask_b32_e32 v0, 0, v0, vcc
	v_fmac_f32_e32 v89, v36, v67
	v_lshlrev_b64 v[34:35], 12, v[34:35]
	v_add_u32_e32 v36, v0, v66
	v_fmac_f32_e32 v144, v37, v67
	v_fmac_f32_e32 v148, v41, v67
	v_lshl_add_u64 v[34:35], s[4:5], 0, v[34:35]
	v_ashrrev_i32_e32 v37, 31, v36
	v_fmac_f32_e32 v145, v38, v67
	v_fmac_f32_e32 v146, v39, v67
	v_fmac_f32_e32 v147, v40, v67
	global_store_dword v[72:73], v177, off offset:128
	global_store_dword v[52:53], v88, off
	global_store_dword v[54:55], v89, off
	global_store_dword v[56:57], v144, off
	global_store_dword v[58:59], v145, off
	global_store_dword v[60:61], v146, off
	global_store_dword v[62:63], v147, off
	global_store_dword v[64:65], v148, off
	global_store_dword v[74:75], v69, off
	global_store_dword v[76:77], v149, off
	global_store_dword v[78:79], v150, off
	global_store_dword v[80:81], v151, off
	global_store_dword v[82:83], v152, off
	global_store_dword v[84:85], v153, off
	global_store_dword v[86:87], v154, off
	global_store_dword v[50:51], v155, off
	v_lshl_add_u64 v[36:37], v[36:37], 2, s[28:29]
	v_lshl_add_u64 v[34:35], v[34:35], 0, v[70:71]
	global_load_dword v68, v[36:37], off
	v_lshl_add_u64 v[36:37], v[34:35], 0, v[94:95]
	v_lshl_add_u64 v[44:45], v[34:35], 0, v[102:103]
	v_lshl_add_u64 v[38:39], v[34:35], 0, v[96:97]
	v_lshl_add_u64 v[40:41], v[34:35], 0, v[98:99]
	v_lshl_add_u64 v[42:43], v[34:35], 0, v[100:101]
	global_load_dword v69, v[36:37], off
	global_load_dword v70, v[38:39], off
	global_load_dword v71, v[40:41], off
	global_load_dword v72, v[42:43], off
	global_load_dword v73, v[44:45], off
	v_lshl_add_u64 v[46:47], v[34:35], 0, v[104:105]
	global_load_dword v74, v[46:47], off
	v_lshl_add_u64 v[48:49], v[34:35], 0, v[106:107]
	global_load_dword v75, v[48:49], off
	v_lshl_add_u64 v[50:51], v[34:35], 0, v[108:109]
	global_load_dword v76, v[50:51], off
	v_lshl_add_u64 v[52:53], v[34:35], 0, v[110:111]
	global_load_dword v77, v[52:53], off
	v_lshl_add_u64 v[54:55], v[34:35], 0, v[112:113]
	global_load_dword v78, v[54:55], off
	v_lshl_add_u64 v[56:57], v[34:35], 0, v[114:115]
	global_load_dword v79, v[56:57], off
	global_load_dword v85, v[36:37], off offset:128
	v_lshl_add_u64 v[58:59], v[34:35], 0, v[116:117]
	global_load_dword v80, v[58:59], off
	v_lshl_add_u64 v[60:61], v[34:35], 0, v[118:119]
	global_load_dword v81, v[60:61], off
	v_lshl_add_u64 v[62:63], v[34:35], 0, v[120:121]
	global_load_dword v82, v[62:63], off
	v_lshl_add_u64 v[64:65], v[34:35], 0, v[122:123]
	global_load_dword v83, v[64:65], off
	v_lshl_add_u64 v[66:67], v[34:35], 0, v[124:125]
	global_load_dword v84, v[66:67], off
	s_waitcnt vmcnt(16)
	v_fmac_f32_e32 v69, v18, v68
	v_add_f32_e32 v18, 0, v22
	s_waitcnt vmcnt(15)
	v_fmac_f32_e32 v70, v19, v68
	s_waitcnt vmcnt(14)
	v_fmac_f32_e32 v71, v20, v68
	s_waitcnt vmcnt(12)
	v_fmac_f32_e32 v73, v18, v68
	v_add_f32_e32 v18, 0, v23
	s_waitcnt vmcnt(11)
	v_fmac_f32_e32 v74, v18, v68
	v_add_f32_e32 v18, 0, v24
	s_waitcnt vmcnt(10)
	v_fmac_f32_e32 v75, v18, v68
	v_add_f32_e32 v18, 0, v25
	s_waitcnt vmcnt(9)
	v_fmac_f32_e32 v76, v18, v68
	v_add_f32_e32 v18, 0, v26
	s_waitcnt vmcnt(8)
	v_fmac_f32_e32 v77, v18, v68
	v_add_f32_e32 v18, 0, v27
	s_waitcnt vmcnt(7)
	v_fmac_f32_e32 v78, v18, v68
	v_add_f32_e32 v18, 0, v28
	s_waitcnt vmcnt(6)
	v_fmac_f32_e32 v79, v18, v68
	v_add_f32_e32 v18, 0, v29
	v_fmac_f32_e32 v72, v21, v68
	s_waitcnt vmcnt(4)
	v_fmac_f32_e32 v80, v18, v68
	v_add_f32_e32 v18, 0, v30
	s_waitcnt vmcnt(3)
	v_fmac_f32_e32 v81, v18, v68
	v_add_f32_e32 v18, 0, v31
	s_waitcnt vmcnt(2)
	v_fmac_f32_e32 v82, v18, v68
	v_add_f32_e32 v18, 0, v32
	global_store_dword v[36:37], v69, off
	global_store_dword v[38:39], v70, off
	global_store_dword v[40:41], v71, off
	global_store_dword v[42:43], v72, off
	s_waitcnt vmcnt(5)
	v_fmac_f32_e32 v83, v18, v68
	v_add_f32_e32 v38, 0, v33
	v_lshl_add_u64 v[18:19], v[34:35], 0, s[0:1]
	v_add_u32_e32 v34, v0, v176
	global_store_dword v[44:45], v73, off
	global_store_dword v[46:47], v74, off
	global_store_dword v[48:49], v75, off
	global_store_dword v[50:51], v76, off
	global_store_dword v[52:53], v77, off
	global_store_dword v[54:55], v78, off
	global_store_dword v[56:57], v79, off
	global_store_dword v[58:59], v80, off
	global_store_dword v[60:61], v81, off
	global_store_dword v[62:63], v82, off
	global_store_dword v[64:65], v83, off
	v_lshl_add_u64 v[20:21], v[18:19], 0, v[96:97]
	s_waitcnt vmcnt(15)
	v_fmac_f32_e32 v84, v38, v68
	v_ashrrev_i32_e32 v35, 31, v34
	v_lshl_add_u64 v[22:23], v[18:19], 0, v[98:99]
	v_lshl_add_u64 v[24:25], v[18:19], 0, v[100:101]
	v_lshl_add_u64 v[26:27], v[18:19], 0, v[102:103]
	v_lshl_add_u64 v[28:29], v[18:19], 0, v[104:105]
	v_lshl_add_u64 v[30:31], v[18:19], 0, v[106:107]
	v_lshl_add_u64 v[32:33], v[18:19], 0, v[108:109]
	global_load_dword v50, v[20:21], off
	global_load_dword v51, v[22:23], off
	global_load_dword v52, v[24:25], off
	global_load_dword v53, v[26:27], off
	global_load_dword v54, v[28:29], off
	global_load_dword v55, v[30:31], off
	global_load_dword v56, v[32:33], off
	v_lshl_add_u64 v[34:35], v[34:35], 2, s[28:29]
	global_store_dword v[66:67], v84, off
	global_load_dword v0, v[34:35], off
	v_lshl_add_u64 v[34:35], v[18:19], 0, v[110:111]
	global_load_dword v57, v[34:35], off
	v_lshl_add_u64 v[38:39], v[18:19], 0, v[112:113]
	global_load_dword v58, v[38:39], off
	v_lshl_add_u64 v[40:41], v[18:19], 0, v[114:115]
	global_load_dword v59, v[40:41], off
	v_lshl_add_u64 v[42:43], v[18:19], 0, v[116:117]
	global_load_dword v60, v[42:43], off
	v_lshl_add_u64 v[44:45], v[18:19], 0, v[118:119]
	global_load_dword v61, v[44:45], off
	v_lshl_add_u64 v[46:47], v[18:19], 0, v[120:121]
	global_load_dword v62, v[46:47], off
	v_lshl_add_u64 v[48:49], v[18:19], 0, v[122:123]
	global_load_dword v63, v[48:49], off
	v_lshl_add_u64 v[18:19], v[18:19], 0, v[124:125]
	global_load_dword v64, v[18:19], off
	s_waitcnt vmcnt(8)
	v_fmac_f32_e32 v85, v2, v0
	v_add_f32_e32 v2, 0, v6
	v_fmac_f32_e32 v53, v2, v0
	v_add_f32_e32 v2, 0, v7
	v_fmac_f32_e32 v54, v2, v0
	v_add_f32_e32 v2, 0, v8
	v_fmac_f32_e32 v55, v2, v0
	v_add_f32_e32 v2, 0, v9
	v_fmac_f32_e32 v56, v2, v0
	v_add_f32_e32 v2, 0, v10
	s_waitcnt vmcnt(7)
	v_fmac_f32_e32 v57, v2, v0
	v_add_f32_e32 v2, 0, v11
	s_waitcnt vmcnt(6)
	v_fmac_f32_e32 v58, v2, v0
	v_add_f32_e32 v2, 0, v12
	s_waitcnt vmcnt(5)
	v_fmac_f32_e32 v59, v2, v0
	v_add_f32_e32 v2, 0, v13
	s_waitcnt vmcnt(4)
	v_fmac_f32_e32 v60, v2, v0
	v_add_f32_e32 v2, 0, v14
	s_waitcnt vmcnt(3)
	v_fmac_f32_e32 v61, v2, v0
	v_add_f32_e32 v2, 0, v15
	s_waitcnt vmcnt(2)
	v_fmac_f32_e32 v62, v2, v0
	v_add_f32_e32 v2, 0, v16
	s_waitcnt vmcnt(1)
	v_fmac_f32_e32 v63, v2, v0
	v_add_f32_e32 v2, 0, v17
	s_waitcnt vmcnt(0)
	v_fmac_f32_e32 v64, v2, v0
	v_fmac_f32_e32 v50, v3, v0
	v_fmac_f32_e32 v51, v4, v0
	v_fmac_f32_e32 v52, v5, v0
	global_store_dword v[36:37], v85, off offset:128
	global_store_dword v[20:21], v50, off
	global_store_dword v[22:23], v51, off
	global_store_dword v[24:25], v52, off
	global_store_dword v[26:27], v53, off
	global_store_dword v[28:29], v54, off
	global_store_dword v[30:31], v55, off
	global_store_dword v[32:33], v56, off
	global_store_dword v[34:35], v57, off
	global_store_dword v[38:39], v58, off
	global_store_dword v[40:41], v59, off
	global_store_dword v[42:43], v60, off
	global_store_dword v[44:45], v61, off
	global_store_dword v[46:47], v62, off
	global_store_dword v[48:49], v63, off
	global_store_dword v[18:19], v64, off
	s_cbranch_scc0 .LBB0_954
